# attention v4: K / V^T staged by LDS-DMA issued at chunk start (no VGPR round trip), v1 key order with per-wave 32-column windows
# speedup vs baseline: 1.0027x; 1.0010x over previous
; __device__ __forceinline__ void attn_phase(const Params& P, char* smem_raw) {
;   u16* sm_k = reinterpret_cast<u16*>(smem_raw);
;   u16* sm_vt = sm_k + 128 * LDSS;
;   u16* sm_p = sm_vt + 64 * 136;
;   float* sm_rpb = reinterpret_cast<float*>(sm_p + 4 * 16 * 136);
;   const int tid = VTID, lane = tid & 63, wid = tid >> 6;
;   const u16* QKV = P.zq;
;   const u16* VTX = P.zf;
;   const u16* VTC = reinterpret_cast<const u16*>(P.summ);
;   uint4 kreg[4], vreg[4];
;   bf16x8 qn[2];
;     ...
;   int dco[4][4];
; #pragma unroll
;   for (int reg = 0; reg < 4; ++reg) {
;     const int c = wid * 16 + (lane >> 4) * 4 + reg;
;     const int cs = min(max(c - 8, 0), 48);
; #pragma unroll
;     for (int q4 = 0; q4 < 4; ++q4) {
;       const int kc = q4 * 16 + (lane & 15);
;       dco[reg][q4] = (kc >= cs && kc < cs + 16) ? (kc - c + 15) : 465;
;     }
;   }
;   int t = VBID;
;   __syncthreads();
;   if (t < 8192) {
;     const int h0 = t & 15;
;     for (int idx = tid; idx < 930; idx += VTHR) sm_rpb[idx] = (idx < 465) ? P.rpb[h0 * 465 + idx] * 1.4426950408889634f : -1e30f;
;     ATT_ISSUE(t, 0)
;     ATT_QLOAD(t)
;   }
.LBB0_1489:
	s_cmp_gt_i32 s34, 12
	s_cselect_b64 s[0:1], -1, 0
	s_cmp_lt_i32 s35, 13
	s_cselect_b64 s[4:5], -1, 0
	s_or_b64 s[0:1], s[0:1], s[4:5]
	s_and_b64 vcc, exec, s[0:1]
	s_cbranch_vccnz .LBB0_1555
	s_waitcnt vmcnt(5)
	v_lshl_add_u32 v109, s2, 1, v153
	s_movk_i32 s0, 0x2000
	v_mov_b32_e32 v0, v153
	v_cmp_gt_i32_e32 vcc, s0, v109
	s_barrier
	s_and_saveexec_b64 s[42:43], vcc
	s_cbranch_execz .LBB0_1501
	v_readlane_b32 s0, v252, 0
	v_readlane_b32 s1, v252, 1
	v_readfirstlane_b32 s3, v153
	s_nop 3
	s_sub_u32 s0, s0, 0x170
	s_subb_u32 s1, s1, 0
	s_load_dwordx2 s[12:13], s[0:1], 0xb8
	s_load_dwordx2 s[8:9], s[0:1], 0x130
	s_load_dwordx4 s[4:7], s[0:1], 0x148
	s_load_dwordx2 s[10:11], s[0:1], 0x158
	s_lshl_b32 s100, s2, 1
	s_add_u32 s3, s100, s3
	s_and_b32 s101, s3, 15
	s_lshl_b32 s3, s3, 8
	s_waitcnt lgkmcnt(0)
	s_lshl_b32 s100, s101, 7
	s_add_u32 s4, s4, s100
	s_addc_u32 s5, s5, 0
	s_add_u32 s10, s10, s100
	s_addc_u32 s11, s11, 0
	s_lshl_b32 s100, s101, 20
	s_add_u32 s6, s6, s100
	s_addc_u32 s7, s7, 0
	s_lshl_b32 s100, s101, 15
	s_add_u32 s8, s8, s100
	s_addc_u32 s9, s9, 0
	s_mul_i32 s100, s101, 0x744
	s_add_u32 s12, s12, s100
	s_addc_u32 s13, s13, 0
	s_bfe_u32 s18, s3, 0x10008
	s_mul_i32 s18, s18, 0x12000
	v_readfirstlane_b32 s100, v204
	s_nop 3
	s_and_b32 s100, s100, 3
	s_lshl_b32 s100, s100, 12
	s_add_u32 s18, s18, s100
	s_add_u32 s18, s18, 16
	v_and_b32_e32 v112, 0xff, v152
	v_and_b32_e32 v113, 63, v152
	v_bfe_u32 v114, v152, 6, 2
	v_lshrrev_b32_e32 v115, 4, v113
	v_and_b32_e32 v116, 15, v113
	v_mul_u32_u24_e32 v117, 0x12000, v153
	v_add_u32_e32 v117, 16, v117
	v_lshrrev_b32_e32 v118, 2, v116
	v_and_b32_e32 v119, 3, v116
	v_lshl_add_u32 v120, v118, 3, v119
	v_bfe_u32 v121, v116, 1, 1
	v_lshl_add_u32 v121, v118, 1, v121
	v_xor_b32_e32 v121, v115, v121
	v_lshl_add_u32 v122, v120, 7, v117
	v_lshl_add_u32 v144, v121, 4, v122
	v_xor_b32_e32 v121, 4, v121
	v_lshl_add_u32 v145, v121, 4, v122
	v_lshrrev_b32_e32 v131, 1, v114
	v_add_u32_e32 v131, v131, v114
	v_add_u32_e32 v132, v131, v118
	v_and_b32_e32 v132, 3, v132
	v_bfe_u32 v133, v116, 1, 1
	v_lshl_add_u32 v132, v132, 1, v133
	v_xor_b32_e32 v132, v115, v132
	v_lshl_add_u32 v133, v131, 3, v120
	v_lshl_add_u32 v133, v133, 7, v117
	v_lshl_add_u32 v224, v132, 4, v133
	v_xor_b32_e32 v132, 4, v132
	v_lshl_add_u32 v225, v132, 4, v133
	v_xor_b32_e32 v123, v115, v119
	v_lshl_add_u32 v124, v116, 8, v117
	v_add_u32_e32 v124, 0x4000, v124
	v_xor_b32_e32 v125, 0, v118
	v_lshl_or_b32 v125, v125, 2, v123
	v_lshl_add_u32 v146, v125, 4, v124
	v_xor_b32_e32 v125, 1, v118
	v_lshl_or_b32 v125, v125, 2, v123
	v_lshl_add_u32 v147, v125, 4, v124
	v_xor_b32_e32 v125, 2, v118
	v_lshl_or_b32 v125, v125, 2, v123
	v_lshl_add_u32 v148, v125, 4, v124
	v_xor_b32_e32 v125, 3, v118
	v_lshl_or_b32 v125, v125, 2, v123
	v_lshl_add_u32 v149, v125, 4, v124
	v_add3_u32 v125, v131, 0, v115
	v_xor_b32_e32 v125, v125, v116
	v_lshl_add_u32 v226, v125, 4, v124
	v_add3_u32 v125, v131, 8, v115
	v_xor_b32_e32 v125, v125, v116
	v_lshl_add_u32 v227, v125, 4, v124
	v_bfe_u32 v126, v113, 3, 3
	v_and_b32_e32 v127, 7, v113
	v_bfe_u32 v128, v113, 4, 1
	v_lshl_add_u32 v129, v114, 5, v126
	v_add_u32_e32 v124, 0, v129
	v_mul_u32_u24_e32 v124, 0x1800, v124
	v_xor_b32_e32 v123, 0, v128
	v_xor_b32_e32 v123, v127, v123
	v_lshl_add_u32 v154, v123, 4, v124
	v_add_u32_e32 v124, 8, v129
	v_mul_u32_u24_e32 v124, 0x1800, v124
	v_xor_b32_e32 v123, 2, v128
	v_xor_b32_e32 v123, v127, v123
	v_lshl_add_u32 v155, v123, 4, v124
	v_add_u32_e32 v124, 16, v129
	v_mul_u32_u24_e32 v124, 0x1800, v124
	v_xor_b32_e32 v123, 4, v128
	v_xor_b32_e32 v123, v127, v123
	v_lshl_add_u32 v156, v123, 4, v124
	v_add_u32_e32 v124, 24, v129
	v_mul_u32_u24_e32 v124, 0x1800, v124
	v_xor_b32_e32 v123, 6, v128
	v_xor_b32_e32 v123, v127, v123
	v_lshl_add_u32 v157, v123, 4, v124
	v_lshrrev_b32_e32 v130, 4, v113
	v_and_b32_e32 v125, 15, v113
	v_lshl_add_u32 v129, v114, 4, v130
	v_add_u32_e32 v124, 0, v129
	v_add_u32_e32 v123, 0, v130
	v_xor_b32_e32 v123, v125, v123
	v_lshlrev_b32_e32 v123, 4, v123
	v_lshl_add_u32 v158, v124, 14, v123
	v_lshl_add_u32 v162, v124, 9, v123
	v_add_u32_e32 v124, 4, v129
	v_add_u32_e32 v123, 4, v130
	v_xor_b32_e32 v123, v125, v123
	v_lshlrev_b32_e32 v123, 4, v123
	v_lshl_add_u32 v159, v124, 14, v123
	v_lshl_add_u32 v163, v124, 9, v123
	v_add_u32_e32 v124, 8, v129
	v_add_u32_e32 v123, 8, v130
	v_xor_b32_e32 v123, v125, v123
	v_lshlrev_b32_e32 v123, 4, v123
	v_lshl_add_u32 v160, v124, 14, v123
	v_lshl_add_u32 v164, v124, 9, v123
	v_add_u32_e32 v124, 12, v129
	v_add_u32_e32 v123, 12, v130
	v_xor_b32_e32 v123, v125, v123
	v_lshlrev_b32_e32 v123, 4, v123
	v_lshl_add_u32 v161, v124, 14, v123
	v_lshl_add_u32 v165, v124, 9, v123
	v_lshl_add_u32 v131, v114, 4, v116
	v_mul_u32_u24_e32 v125, 0x1800, v131
	v_lshl_add_u32 v166, v115, 4, v125
	v_lshlrev_b32_e32 v125, 11, v131
	v_lshl_add_u32 v167, v115, 3, v125
	v_sub_u32_e64 v132, v131, 8 clamp
	v_min_u32_e32 v132, 48, v132
	v_lshrrev_b32_e32 v133, 1, v114
	v_add_u32_e32 v133, v133, v114
	v_add_u32_e32 v133, v133, v115
	v_lshlrev_b32_e32 v133, 3, v133
	v_mov_b32_e32 v210, 0x7c
	v_add_u32_e32 v134, 0, v133
	v_sub_u32_e32 v135, v134, v132
	v_cmp_gt_u32_e32 vcc, 16, v135
	v_sub_u32_e32 v136, v134, v131
	v_lshlrev_b32_e32 v136, 2, v136
	v_add_u32_e32 v136, 60, v136
	v_cndmask_b32_e32 v168, v210, v136, vcc
	v_add_u32_e32 v134, 1, v133
	v_sub_u32_e32 v135, v134, v132
	v_cmp_gt_u32_e32 vcc, 16, v135
	v_sub_u32_e32 v136, v134, v131
	v_lshlrev_b32_e32 v136, 2, v136
	v_add_u32_e32 v136, 60, v136
	v_cndmask_b32_e32 v169, v210, v136, vcc
	v_add_u32_e32 v134, 2, v133
	v_sub_u32_e32 v135, v134, v132
	v_cmp_gt_u32_e32 vcc, 16, v135
; __device__ __forceinline__ void attn_phase(const Params& P, char* smem_raw) {
;     ...
;   int dco[4][4];
; #pragma unroll
;   for (int reg = 0; reg < 4; ++reg) {
;     const int c = wid * 16 + (lane >> 4) * 4 + reg;
;     const int cs = min(max(c - 8, 0), 48);
; #pragma unroll
;     for (int q4 = 0; q4 < 4; ++q4) {
;       const int kc = q4 * 16 + (lane & 15);
;       dco[reg][q4] = (kc >= cs && kc < cs + 16) ? (kc - c + 15) : 465;
;     }
;   }
;   int t = VBID;
;   __syncthreads();
;   if (t < 8192) {
;     const int h0 = t & 15;
;     for (int idx = tid; idx < 930; idx += VTHR) sm_rpb[idx] = (idx < 465) ? P.rpb[h0 * 465 + idx] * 1.4426950408889634f : -1e30f;
;     ATT_ISSUE(t, 0)
;     ATT_QLOAD(t)
;   }
	v_sub_u32_e32 v136, v134, v131
	v_lshlrev_b32_e32 v136, 2, v136
	v_add_u32_e32 v136, 60, v136
	v_cndmask_b32_e32 v170, v210, v136, vcc
	v_add_u32_e32 v134, 3, v133
	v_sub_u32_e32 v135, v134, v132
	v_cmp_gt_u32_e32 vcc, 16, v135
	v_sub_u32_e32 v136, v134, v131
	v_lshlrev_b32_e32 v136, 2, v136
	v_add_u32_e32 v136, 60, v136
	v_cndmask_b32_e32 v171, v210, v136, vcc
	v_add_u32_e32 v134, 4, v133
	v_sub_u32_e32 v135, v134, v132
	v_cmp_gt_u32_e32 vcc, 16, v135
	v_sub_u32_e32 v136, v134, v131
	v_lshlrev_b32_e32 v136, 2, v136
	v_add_u32_e32 v136, 60, v136
	v_cndmask_b32_e32 v172, v210, v136, vcc
	v_add_u32_e32 v134, 5, v133
	v_sub_u32_e32 v135, v134, v132
	v_cmp_gt_u32_e32 vcc, 16, v135
	v_sub_u32_e32 v136, v134, v131
	v_lshlrev_b32_e32 v136, 2, v136
	v_add_u32_e32 v136, 60, v136
	v_cndmask_b32_e32 v173, v210, v136, vcc
	v_add_u32_e32 v134, 6, v133
	v_sub_u32_e32 v135, v134, v132
	v_cmp_gt_u32_e32 vcc, 16, v135
	v_sub_u32_e32 v136, v134, v131
	v_lshlrev_b32_e32 v136, 2, v136
	v_add_u32_e32 v136, 60, v136
	v_cndmask_b32_e32 v174, v210, v136, vcc
	v_add_u32_e32 v134, 7, v133
	v_sub_u32_e32 v135, v134, v132
	v_cmp_gt_u32_e32 vcc, 16, v135
	v_sub_u32_e32 v136, v134, v131
	v_lshlrev_b32_e32 v136, 2, v136
	v_add_u32_e32 v136, 60, v136
	v_cndmask_b32_e32 v175, v210, v136, vcc
	v_mov_b32_e32 v143, 0xf149f2ca
	v_mov_b32_e32 v137, v112
	v_lshrrev_b32_e32 v138, 5, v137
	v_and_b32_e32 v139, 31, v137
	v_mul_u32_u24_e32 v140, 31, v138
	v_add_u32_e32 v140, v140, v139
	v_min_u32_e32 v140, 0x1d0, v140
	v_lshlrev_b32_e32 v140, 2, v140
	global_load_dword v141, v140, s[12:13]
	v_lshl_add_u32 v142, v137, 2, v117
	v_add_u32_e32 v142, 0x10000, v142
	v_cmp_eq_u32_e32 vcc, 31, v139
	s_waitcnt vmcnt(0)
	v_mul_f32_e32 v141, 0x3fb8aa3b, v141
	v_cndmask_b32_e32 v141, v141, v143, vcc
	ds_write_b32 v142, v141
	v_add_u32_e32 v137, 0x100, v112
	v_lshrrev_b32_e32 v138, 5, v137
	v_and_b32_e32 v139, 31, v137
	v_mul_u32_u24_e32 v140, 31, v138
	v_add_u32_e32 v140, v140, v139
	v_min_u32_e32 v140, 0x1d0, v140
	v_lshlrev_b32_e32 v140, 2, v140
	global_load_dword v141, v140, s[12:13]
	v_lshl_add_u32 v142, v137, 2, v117
	v_add_u32_e32 v142, 0x10000, v142
	v_cmp_eq_u32_e32 vcc, 31, v139
	s_waitcnt vmcnt(0)
	v_mul_f32_e32 v141, 0x3fb8aa3b, v141
	v_cndmask_b32_e32 v141, v141, v143, vcc
	ds_write_b32 v142, v141
	s_and_b32 s0, s3, 0xff
	s_lshr_b32 s1, s0, 2
	s_and_b32 s0, s0, 3
	s_lshl_b32 s0, s0, 5
	s_lshr_b32 vcc_lo, s3, 12
	s_add_u32 s0, s0, vcc_lo
	s_sub_i32 vcc_lo, s0, 4
	s_max_i32 vcc_lo, vcc_lo, 0
	s_min_i32 vcc_lo, vcc_lo, 0x78
	s_lshl_b32 vcc_hi, s1, 13
	s_lshl_b32 m0, vcc_lo, 6
	s_add_u32 m0, m0, vcc_hi
	s_mul_i32 m0, m0, 0x1800
	s_add_u32 s12, s4, m0
	s_addc_u32 s13, s5, 0
	s_lshl_b32 m0, s1, 24
	s_lshl_b32 s100, vcc_lo, 7
	s_add_u32 m0, m0, s100
	s_add_u32 s14, s6, m0
	s_addc_u32 s15, s7, 0
	s_lshl_b32 m0, s0, 6
	s_add_u32 m0, m0, vcc_hi
	s_mul_i32 m0, m0, 0x1800
	s_add_u32 s100, s4, m0
	s_addc_u32 s101, s5, 0
	global_load_dwordx4 v[64:67], v166, s[100:101]
	global_load_dwordx4 v[68:71], v166, s[100:101] offset:64
	s_and_b32 s0, s3, 0xff
	s_lshr_b32 s1, s0, 2
	s_and_b32 s0, s0, 3
	s_lshl_b32 s0, s0, 5
	s_lshr_b32 vcc_lo, s3, 12
	s_add_u32 s0, s0, vcc_lo
	s_sub_i32 vcc_lo, s0, 4
	s_max_i32 vcc_lo, vcc_lo, 0
	s_min_i32 vcc_lo, vcc_lo, 0x78
	s_lshl_b32 vcc_hi, s1, 13
	s_sub_i32 vcc_lo, vcc_lo, s0
	s_add_i32 vcc_lo, vcc_lo, 4
	s_lshl_b32 vcc_lo, vcc_lo, 7
	s_bfe_u32 m0, s3, 0x10008
	s_mul_i32 m0, m0, 0x12000
	s_add_i32 vcc_lo, vcc_lo, m0
	s_add_i32 vcc_lo, vcc_lo, 0x10010
	v_add_u32_e32 v184, vcc_lo, v168
	v_add_u32_e32 v185, vcc_lo, v169
	v_add_u32_e32 v186, vcc_lo, v170
	v_add_u32_e32 v187, vcc_lo, v171
	v_add_u32_e32 v188, vcc_lo, v172
	v_add_u32_e32 v189, vcc_lo, v173
	v_add_u32_e32 v190, vcc_lo, v174
	v_add_u32_e32 v191, vcc_lo, v175
	s_add_u32 s100, s12, 0x800
	s_addc_u32 s101, s13, 0
	s_mov_b64 s[0:1], s[14:15]
	s_add_u32 m0, s18, 0x0
	s_nop 0
	v_mad_u64_u32 v[230:231], vcc, v154, 1, s[100:101]
	global_load_lds_dwordx4 v[230:231], off
	s_add_u32 m0, s18, 0x4000
	s_nop 0
	v_mad_u64_u32 v[232:233], vcc, v158, 1, s[0:1]
	global_load_lds_dwordx4 v[232:233], off
	s_add_u32 m0, s18, 0x400
	s_nop 0
	v_mad_u64_u32 v[230:231], vcc, v155, 1, s[100:101]
	global_load_lds_dwordx4 v[230:231], off
	s_add_u32 m0, s18, 0x4400
	s_nop 0
	v_mad_u64_u32 v[232:233], vcc, v159, 1, s[0:1]
	global_load_lds_dwordx4 v[232:233], off
	s_add_u32 m0, s18, 0x800
	s_nop 0
	v_mad_u64_u32 v[230:231], vcc, v156, 1, s[100:101]
	global_load_lds_dwordx4 v[230:231], off
	s_add_u32 m0, s18, 0x4800
	s_nop 0
	v_mad_u64_u32 v[232:233], vcc, v160, 1, s[0:1]
	global_load_lds_dwordx4 v[232:233], off
	s_add_u32 m0, s18, 0xc00
	s_nop 0
	v_mad_u64_u32 v[230:231], vcc, v157, 1, s[100:101]
	global_load_lds_dwordx4 v[230:231], off
	s_add_u32 m0, s18, 0x4c00
	s_nop 0
	v_mad_u64_u32 v[232:233], vcc, v161, 1, s[0:1]
	global_load_lds_dwordx4 v[232:233], off
	v_mov_b32_e32 v200, 0xf149f2ca
	v_mov_b32_e32 v201, 0
	v_mov_b32_e32 v32, 0
	v_mov_b32_e32 v33, 0
	v_mov_b32_e32 v34, 0
	v_mov_b32_e32 v35, 0
	v_mov_b32_e32 v36, 0
	v_mov_b32_e32 v37, 0
	v_mov_b32_e32 v38, 0
	v_mov_b32_e32 v39, 0
	v_mov_b32_e32 v40, 0
	v_mov_b32_e32 v41, 0
	v_mov_b32_e32 v42, 0
	v_mov_b32_e32 v43, 0
	v_mov_b32_e32 v44, 0
	v_mov_b32_e32 v45, 0
	v_mov_b32_e32 v46, 0
	v_mov_b32_e32 v47, 0
	s_waitcnt vmcnt(0)
	s_waitcnt lgkmcnt(0)
	s_barrier
	ds_read_b32 v0, v184 offset:384
	ds_read_b32 v1, v185 offset:384
	ds_read_b32 v2, v186 offset:384
	ds_read_b32 v3, v187 offset:384
	ds_read_b32 v4, v188 offset:384
	ds_read_b32 v5, v189 offset:384
	ds_read_b32 v6, v190 offset:384
	ds_read_b32 v7, v191 offset:384
	ds_read_b32 v8, v184 offset:512
	ds_read_b32 v9, v185 offset:512
	ds_read_b32 v10, v186 offset:512
	ds_read_b32 v11, v187 offset:512
	ds_read_b32 v12, v188 offset:512
	ds_read_b32 v13, v189 offset:512
	ds_read_b32 v14, v190 offset:512
	ds_read_b32 v15, v191 offset:512
	s_waitcnt lgkmcnt(0)
; __device__ __forceinline__ void attn_phase(const Params& P, char* smem_raw) {
;     ...
;       }
;       __syncthreads();
;       f32x4 sacc[8];
; #pragma unroll
;       for (int t8 = 0; t8 < 8; ++t8) sacc[t8] = f32x4{0.f, 0.f, 0.f, 0.f};
; #pragma unroll
;       for (int s = 0; s < 2; ++s)
; #pragma unroll
;         for (int t8 = 0; t8 < 8; ++t8) {
;           const bf16x8 kf = *reinterpret_cast<const bf16x8*>(&sm_k[(t8 * 16 + (lane_c & 15)) * LDSS + s * 32 + (lane_c >> 4) * 8]);
;           sacc[t8] = __builtin_amdgcn_mfma_f32_16x16x32_bf16(qf[s], kf, sacc[t8], 0, 0, 0);
;         }
;       if (ck < 5) {
;         ATT_ISSUE(t, ck + 1)
;       } else if (t + VGRID < 8192) {
;         ATT_ISSUE(t + VGRID, 0)
;         ATT_QLOAD(t + VGRID)
;       }
;       if (ck < 4) {
;         const float* rb0 = sm_rpb + (rs + ck * 2 - r + 7) * 31;
; #pragma unroll
;         for (int t8 = 0; t8 < 8; ++t8)
; #pragma unroll
;           for (int reg = 0; reg < 4; ++reg)
;             sacc[t8][reg] += rb0[(t8 >> 2) * 31 + dco[reg][t8 & 3]];
;       }
; #pragma unroll
;       for (int reg = 0; reg < 4; ++reg) {
;         float mx = sacc[0][reg];
; #pragma unroll
;         for (int t8 = 1; t8 < 8; ++t8) mx = fmaxf(mx, sacc[t8][reg]);
;         mx = row16_max(mx);
;         const float mnew = fmaxf(mrow[reg], mx);
;         const float alpha = __builtin_amdgcn_exp2f(mrow[reg] - mnew);
;         mrow[reg] = mnew;
;         float rsum = 0.f;
; #pragma unroll
;         for (int t8 = 0; t8 < 8; ++t8) {
;           const float p = __builtin_amdgcn_exp2f(sacc[t8][reg] - mnew);
;           rsum += p;
;           sm_p[(wid * 16 + (lane_c >> 4) * 4 + reg) * 136 + t8 * 16 + (lane_c & 15)] = f2bf(p);
;         }
;         rsum = row16_sum(rsum);
;         lrow[reg] = lrow[reg] * alpha + rsum;
; #pragma unroll
;         for (int td = 0; td < 4; ++td) o[td][reg] *= alpha;
;       }
;       asm volatile("s_waitcnt lgkmcnt(0)" ::: "memory");
; #pragma unroll
;       for (int s4 = 0; s4 < 4; ++s4) {
;         const bf16x8 pf = *reinterpret_cast<const bf16x8*>(&sm_p[(wid * 16 + (lane_c & 15)) * 136 + s4 * 32 + (lane_c >> 4) * 8]);
; #pragma unroll
;         for (int td = 0; td < 4; ++td) {
;           const bf16x8 vf = *reinterpret_cast<const bf16x8*>(&sm_vt[(td * 16 + (lane_c & 15)) * 136 + s4 * 32 + (lane_c >> 4) * 8]);
.Lmy_att_tile:
	s_barrier
	s_add_u32 s100, s12, 0xc0800
	s_addc_u32 s101, s13, 0
	s_add_u32 s0, s14, 0x100
	s_addc_u32 s1, s15, 0
	s_add_u32 m0, s18, 0x8000
	s_nop 0
	v_mad_u64_u32 v[230:231], vcc, v154, 1, s[100:101]
	global_load_lds_dwordx4 v[230:231], off
	s_add_u32 m0, s18, 0xc000
	s_nop 0
	v_mad_u64_u32 v[232:233], vcc, v158, 1, s[0:1]
	global_load_lds_dwordx4 v[232:233], off
	s_add_u32 m0, s18, 0x8400
	s_nop 0
	v_mad_u64_u32 v[230:231], vcc, v155, 1, s[100:101]
	global_load_lds_dwordx4 v[230:231], off
	s_add_u32 m0, s18, 0xc400
	s_nop 0
	v_mad_u64_u32 v[232:233], vcc, v159, 1, s[0:1]
	global_load_lds_dwordx4 v[232:233], off
	s_add_u32 m0, s18, 0x8800
	s_nop 0
	v_mad_u64_u32 v[230:231], vcc, v156, 1, s[100:101]
	global_load_lds_dwordx4 v[230:231], off
	s_add_u32 m0, s18, 0xc800
	s_nop 0
	v_mad_u64_u32 v[232:233], vcc, v160, 1, s[0:1]
	global_load_lds_dwordx4 v[232:233], off
	s_add_u32 m0, s18, 0x8c00
	s_nop 0
	v_mad_u64_u32 v[230:231], vcc, v157, 1, s[100:101]
	global_load_lds_dwordx4 v[230:231], off
	s_add_u32 m0, s18, 0xcc00
	s_nop 0
	v_mad_u64_u32 v[232:233], vcc, v161, 1, s[0:1]
	global_load_lds_dwordx4 v[232:233], off
	ds_read_b128 v[112:115], v224 offset:0
	ds_read_b128 v[116:119], v225 offset:0
	ds_read_b128 v[120:123], v224 offset:512
	ds_read_b128 v[124:127], v225 offset:512
	ds_read_b128 v[128:131], v224 offset:8192
	ds_read_b128 v[132:135], v225 offset:8192
	ds_read_b128 v[136:139], v224 offset:8704
	ds_read_b128 v[140:143], v225 offset:8704
	s_waitcnt lgkmcnt(7)
	v_mfma_f32_16x16x32_bf16 v[0:3], v[112:115], v[64:67], v[0:3]
	s_waitcnt lgkmcnt(6)
	v_mfma_f32_16x16x32_bf16 v[0:3], v[116:119], v[68:71], v[0:3]
	s_waitcnt lgkmcnt(5)
	v_mfma_f32_16x16x32_bf16 v[4:7], v[120:123], v[64:67], v[4:7]
	s_waitcnt lgkmcnt(4)
	v_mfma_f32_16x16x32_bf16 v[4:7], v[124:127], v[68:71], v[4:7]
	s_waitcnt lgkmcnt(3)
	v_mfma_f32_16x16x32_bf16 v[8:11], v[128:131], v[64:67], v[8:11]
	s_waitcnt lgkmcnt(2)
	v_mfma_f32_16x16x32_bf16 v[8:11], v[132:135], v[68:71], v[8:11]
	s_waitcnt lgkmcnt(1)
	v_mfma_f32_16x16x32_bf16 v[12:15], v[136:139], v[64:67], v[12:15]
	s_waitcnt lgkmcnt(0)
	v_mfma_f32_16x16x32_bf16 v[12:15], v[140:143], v[68:71], v[12:15]
	s_nop 7
	v_max3_f32 v203, v0, v1, v2
	v_max3_f32 v203, v203, v3, v4
	v_max3_f32 v203, v203, v5, v6
	v_max3_f32 v203, v203, v7, v8
	v_max3_f32 v203, v203, v9, v10
	v_max3_f32 v203, v203, v11, v12
	v_max3_f32 v203, v203, v13, v14
	v_max_f32_e32 v203, v203, v15
	v_mov_b32_e32 v205, v203
	s_nop 1
	v_permlane16_swap_b32_e32 v203, v205
	v_max_f32_e32 v203, v203, v205
	v_mov_b32_e32 v205, v203
	s_nop 1
	v_permlane32_swap_b32_e32 v203, v205
	v_max_f32_e32 v203, v203, v205
	v_max_f32_e32 v218, v200, v203
	v_sub_f32_e32 v220, v200, v218
	v_mov_b32_e32 v219, v218
	v_exp_f32_e32 v220, v220
	v_mov_b32_e32 v200, v218
	v_pk_add_f32 v[0:1], v[0:1], v[218:219] neg_lo:[0,1] neg_hi:[0,1]
	v_pk_add_f32 v[2:3], v[2:3], v[218:219] neg_lo:[0,1] neg_hi:[0,1]
	v_pk_add_f32 v[4:5], v[4:5], v[218:219] neg_lo:[0,1] neg_hi:[0,1]
	v_pk_add_f32 v[6:7], v[6:7], v[218:219] neg_lo:[0,1] neg_hi:[0,1]
	v_pk_add_f32 v[8:9], v[8:9], v[218:219] neg_lo:[0,1] neg_hi:[0,1]
	v_pk_add_f32 v[10:11], v[10:11], v[218:219] neg_lo:[0,1] neg_hi:[0,1]
	v_pk_add_f32 v[12:13], v[12:13], v[218:219] neg_lo:[0,1] neg_hi:[0,1]
	v_pk_add_f32 v[14:15], v[14:15], v[218:219] neg_lo:[0,1] neg_hi:[0,1]
	v_exp_f32_e32 v0, v0
	v_exp_f32_e32 v1, v1
	v_exp_f32_e32 v2, v2
	v_exp_f32_e32 v3, v3
	v_exp_f32_e32 v4, v4
	v_exp_f32_e32 v5, v5
	v_exp_f32_e32 v6, v6
	v_exp_f32_e32 v7, v7
	v_exp_f32_e32 v8, v8
	v_exp_f32_e32 v9, v9
	v_exp_f32_e32 v10, v10
	v_exp_f32_e32 v11, v11
	v_exp_f32_e32 v12, v12
	v_exp_f32_e32 v13, v13
	v_exp_f32_e32 v14, v14
	v_exp_f32_e32 v15, v15
	s_and_b32 s0, s3, 0xff
	s_lshr_b32 s1, s0, 2
	s_and_b32 s0, s0, 3
	s_lshl_b32 s0, s0, 5
	s_lshr_b32 vcc_lo, s3, 12
	s_add_u32 s0, s0, vcc_lo
	s_sub_i32 vcc_lo, s0, 4
	s_max_i32 vcc_lo, vcc_lo, 0
	s_min_i32 vcc_lo, vcc_lo, 0x78
	s_lshl_b32 vcc_hi, s1, 13
	s_lshl_b32 m0, s1, 8
	s_add_u32 m0, m0, 0x8000
	s_mul_i32 m0, m0, 0x1800
	s_add_u32 s16, s4, m0
	s_addc_u32 s17, s5, 0
	s_lshl_b32 m0, s1, 19
	s_add_u32 s36, s8, m0
	s_addc_u32 s37, s9, 0
	s_lshl_b32 m0, s0, 6
	s_add_u32 m0, m0, vcc_hi
	s_lshl_b32 m0, m0, 11
	s_add_u32 s98, s10, m0
	s_addc_u32 s99, s11, 0
	ds_read_b128 v[112:115], v226 offset:0
	ds_read_b128 v[116:119], v226 offset:4096
	ds_read_b128 v[120:123], v226 offset:8192
	ds_read_b128 v[124:127], v226 offset:12288
	ds_read_b128 v[128:131], v227 offset:0
	ds_read_b128 v[132:135], v227 offset:4096
	ds_read_b128 v[136:139], v227 offset:8192
	ds_read_b128 v[140:143], v227 offset:12288
	v_mov_b32_e32 v221, v220
	v_pk_add_f32 v[222:223], v[0:1], v[2:3]
	v_pk_add_f32 v[222:223], v[222:223], v[4:5]
	v_pk_add_f32 v[222:223], v[222:223], v[6:7]
	v_pk_add_f32 v[222:223], v[222:223], v[8:9]
	v_pk_add_f32 v[222:223], v[222:223], v[10:11]
	v_pk_add_f32 v[222:223], v[222:223], v[12:13]
	v_pk_add_f32 v[222:223], v[222:223], v[14:15]
	v_pk_mul_f32 v[32:33], v[32:33], v[220:221]
	v_pk_mul_f32 v[34:35], v[34:35], v[220:221]
	v_pk_mul_f32 v[36:37], v[36:37], v[220:221]
	v_pk_mul_f32 v[38:39], v[38:39], v[220:221]
	v_pk_mul_f32 v[40:41], v[40:41], v[220:221]
	v_pk_mul_f32 v[42:43], v[42:43], v[220:221]
	v_pk_mul_f32 v[44:45], v[44:45], v[220:221]
	v_pk_mul_f32 v[46:47], v[46:47], v[220:221]
	v_add_f32_e32 v203, v222, v223
	v_fma_f32 v201, v201, v220, v203
	v_cvt_pk_bf16_f32 v48, v0, v1
	v_cvt_pk_bf16_f32 v49, v2, v3
	v_cvt_pk_bf16_f32 v50, v4, v5
	v_cvt_pk_bf16_f32 v51, v6, v7
	v_cvt_pk_bf16_f32 v52, v8, v9
	v_cvt_pk_bf16_f32 v53, v10, v11
	v_cvt_pk_bf16_f32 v54, v12, v13
	v_cvt_pk_bf16_f32 v55, v14, v15
	s_waitcnt lgkmcnt(7)
	v_mfma_f32_16x16x32_bf16 v[32:35], v[112:115], v[48:51], v[32:35]
	s_waitcnt lgkmcnt(6)
	v_mfma_f32_16x16x32_bf16 v[36:39], v[116:119], v[48:51], v[36:39]
	s_waitcnt lgkmcnt(5)
	v_mfma_f32_16x16x32_bf16 v[40:43], v[120:123], v[48:51], v[40:43]
	s_waitcnt lgkmcnt(4)
	v_mfma_f32_16x16x32_bf16 v[44:47], v[124:127], v[48:51], v[44:47]
	s_waitcnt lgkmcnt(3)
	v_mfma_f32_16x16x32_bf16 v[32:35], v[128:131], v[52:55], v[32:35]
	s_waitcnt lgkmcnt(2)
	v_mfma_f32_16x16x32_bf16 v[36:39], v[132:135], v[52:55], v[36:39]
	s_waitcnt lgkmcnt(1)
	v_mfma_f32_16x16x32_bf16 v[40:43], v[136:139], v[52:55], v[40:43]
	s_waitcnt lgkmcnt(0)
	v_mfma_f32_16x16x32_bf16 v[44:47], v[140:143], v[52:55], v[44:47]
	ds_read_b32 v0, v184 offset:640
	ds_read_b32 v1, v185 offset:640
	ds_read_b32 v2, v186 offset:640
	ds_read_b32 v3, v187 offset:640
	ds_read_b32 v4, v188 offset:640
	ds_read_b32 v5, v189 offset:640
	ds_read_b32 v6, v190 offset:640
	ds_read_b32 v7, v191 offset:640
	ds_read_b32 v8, v184 offset:768
	ds_read_b32 v9, v185 offset:768
	ds_read_b32 v10, v186 offset:768
	ds_read_b32 v11, v187 offset:768
	ds_read_b32 v12, v188 offset:768
	ds_read_b32 v13, v189 offset:768
	ds_read_b32 v14, v190 offset:768
	ds_read_b32 v15, v191 offset:768
	s_waitcnt vmcnt(0)
	s_waitcnt lgkmcnt(0)
	s_barrier
; __device__ __forceinline__ void attn_phase(const Params& P, char* smem_raw) {
;     ...
;       __syncthreads();
;       f32x4 sacc[8];
; #pragma unroll
;       for (int t8 = 0; t8 < 8; ++t8) sacc[t8] = f32x4{0.f, 0.f, 0.f, 0.f};
; #pragma unroll
;       for (int s = 0; s < 2; ++s)
; #pragma unroll
;         for (int t8 = 0; t8 < 8; ++t8) {
;           const bf16x8 kf = *reinterpret_cast<const bf16x8*>(&sm_k[(t8 * 16 + (lane_c & 15)) * LDSS + s * 32 + (lane_c >> 4) * 8]);
;           sacc[t8] = __builtin_amdgcn_mfma_f32_16x16x32_bf16(qf[s], kf, sacc[t8], 0, 0, 0);
;         }
;       if (ck < 5) {
;         ATT_ISSUE(t, ck + 1)
;       } else if (t + VGRID < 8192) {
;         ATT_ISSUE(t + VGRID, 0)
;         ATT_QLOAD(t + VGRID)
;       }
;       if (ck < 4) {
;         const float* rb0 = sm_rpb + (rs + ck * 2 - r + 7) * 31;
; #pragma unroll
;         for (int t8 = 0; t8 < 8; ++t8)
; #pragma unroll
;           for (int reg = 0; reg < 4; ++reg)
;             sacc[t8][reg] += rb0[(t8 >> 2) * 31 + dco[reg][t8 & 3]];
;       }
; #pragma unroll
;       for (int reg = 0; reg < 4; ++reg) {
;         float mx = sacc[0][reg];
; #pragma unroll
;         for (int t8 = 1; t8 < 8; ++t8) mx = fmaxf(mx, sacc[t8][reg]);
;         mx = row16_max(mx);
;         const float mnew = fmaxf(mrow[reg], mx);
;         const float alpha = __builtin_amdgcn_exp2f(mrow[reg] - mnew);
;         mrow[reg] = mnew;
;         float rsum = 0.f;
; #pragma unroll
;         for (int t8 = 0; t8 < 8; ++t8) {
;           const float p = __builtin_amdgcn_exp2f(sacc[t8][reg] - mnew);
;           rsum += p;
;           sm_p[(wid * 16 + (lane_c >> 4) * 4 + reg) * 136 + t8 * 16 + (lane_c & 15)] = f2bf(p);
;         }
;         rsum = row16_sum(rsum);
;         lrow[reg] = lrow[reg] * alpha + rsum;
; #pragma unroll
;         for (int td = 0; td < 4; ++td) o[td][reg] *= alpha;
;       }
;       asm volatile("s_waitcnt lgkmcnt(0)" ::: "memory");
; #pragma unroll
;       for (int s4 = 0; s4 < 4; ++s4) {
;         const bf16x8 pf = *reinterpret_cast<const bf16x8*>(&sm_p[(wid * 16 + (lane_c & 15)) * 136 + s4 * 32 + (lane_c >> 4) * 8]);
; #pragma unroll
;         for (int td = 0; td < 4; ++td) {
;           const bf16x8 vf = *reinterpret_cast<const bf16x8*>(&sm_vt[(td * 16 + (lane_c & 15)) * 136 + s4 * 32 + (lane_c >> 4) * 8]);
;           o[td] = __builtin_amdgcn_mfma_f32_16x16x32_bf16(pf, vf, o[td], 0, 0, 0);
	s_add_u32 s100, s12, 0x180800
	s_addc_u32 s101, s13, 0
	s_add_u32 s0, s14, 0x200
	s_addc_u32 s1, s15, 0
	s_add_u32 m0, s18, 0x0
	s_nop 0
	v_mad_u64_u32 v[230:231], vcc, v154, 1, s[100:101]
	global_load_lds_dwordx4 v[230:231], off
	s_add_u32 m0, s18, 0x4000
	s_nop 0
	v_mad_u64_u32 v[232:233], vcc, v158, 1, s[0:1]
	global_load_lds_dwordx4 v[232:233], off
	s_add_u32 m0, s18, 0x400
	s_nop 0
	v_mad_u64_u32 v[230:231], vcc, v155, 1, s[100:101]
	global_load_lds_dwordx4 v[230:231], off
	s_add_u32 m0, s18, 0x4400
	s_nop 0
	v_mad_u64_u32 v[232:233], vcc, v159, 1, s[0:1]
	global_load_lds_dwordx4 v[232:233], off
	s_add_u32 m0, s18, 0x800
	s_nop 0
	v_mad_u64_u32 v[230:231], vcc, v156, 1, s[100:101]
	global_load_lds_dwordx4 v[230:231], off
	s_add_u32 m0, s18, 0x4800
	s_nop 0
	v_mad_u64_u32 v[232:233], vcc, v160, 1, s[0:1]
	global_load_lds_dwordx4 v[232:233], off
	s_add_u32 m0, s18, 0xc00
	s_nop 0
	v_mad_u64_u32 v[230:231], vcc, v157, 1, s[100:101]
	global_load_lds_dwordx4 v[230:231], off
	s_add_u32 m0, s18, 0x4c00
	s_nop 0
	v_mad_u64_u32 v[232:233], vcc, v161, 1, s[0:1]
	global_load_lds_dwordx4 v[232:233], off
	ds_read_b128 v[112:115], v224 offset:32768
	ds_read_b128 v[116:119], v225 offset:32768
	ds_read_b128 v[120:123], v224 offset:33280
	ds_read_b128 v[124:127], v225 offset:33280
	ds_read_b128 v[128:131], v224 offset:40960
	ds_read_b128 v[132:135], v225 offset:40960
	ds_read_b128 v[136:139], v224 offset:41472
	ds_read_b128 v[140:143], v225 offset:41472
	s_waitcnt lgkmcnt(7)
	v_mfma_f32_16x16x32_bf16 v[0:3], v[112:115], v[64:67], v[0:3]
	s_waitcnt lgkmcnt(6)
	v_mfma_f32_16x16x32_bf16 v[0:3], v[116:119], v[68:71], v[0:3]
	s_waitcnt lgkmcnt(5)
	v_mfma_f32_16x16x32_bf16 v[4:7], v[120:123], v[64:67], v[4:7]
	s_waitcnt lgkmcnt(4)
	v_mfma_f32_16x16x32_bf16 v[4:7], v[124:127], v[68:71], v[4:7]
	s_waitcnt lgkmcnt(3)
	v_mfma_f32_16x16x32_bf16 v[8:11], v[128:131], v[64:67], v[8:11]
	s_waitcnt lgkmcnt(2)
	v_mfma_f32_16x16x32_bf16 v[8:11], v[132:135], v[68:71], v[8:11]
	s_waitcnt lgkmcnt(1)
	v_mfma_f32_16x16x32_bf16 v[12:15], v[136:139], v[64:67], v[12:15]
	s_waitcnt lgkmcnt(0)
	v_mfma_f32_16x16x32_bf16 v[12:15], v[140:143], v[68:71], v[12:15]
	s_nop 7
	v_max3_f32 v203, v0, v1, v2
	v_max3_f32 v203, v203, v3, v4
	v_max3_f32 v203, v203, v5, v6
	v_max3_f32 v203, v203, v7, v8
	v_max3_f32 v203, v203, v9, v10
	v_max3_f32 v203, v203, v11, v12
	v_max3_f32 v203, v203, v13, v14
	v_max_f32_e32 v203, v203, v15
	v_mov_b32_e32 v205, v203
	s_nop 1
	v_permlane16_swap_b32_e32 v203, v205
	v_max_f32_e32 v203, v203, v205
	v_mov_b32_e32 v205, v203
	s_nop 1
	v_permlane32_swap_b32_e32 v203, v205
	v_max_f32_e32 v203, v203, v205
	v_max_f32_e32 v218, v200, v203
	v_sub_f32_e32 v220, v200, v218
	v_mov_b32_e32 v219, v218
	v_exp_f32_e32 v220, v220
	v_mov_b32_e32 v200, v218
	v_pk_add_f32 v[0:1], v[0:1], v[218:219] neg_lo:[0,1] neg_hi:[0,1]
	v_pk_add_f32 v[2:3], v[2:3], v[218:219] neg_lo:[0,1] neg_hi:[0,1]
	v_pk_add_f32 v[4:5], v[4:5], v[218:219] neg_lo:[0,1] neg_hi:[0,1]
	v_pk_add_f32 v[6:7], v[6:7], v[218:219] neg_lo:[0,1] neg_hi:[0,1]
	v_pk_add_f32 v[8:9], v[8:9], v[218:219] neg_lo:[0,1] neg_hi:[0,1]
	v_pk_add_f32 v[10:11], v[10:11], v[218:219] neg_lo:[0,1] neg_hi:[0,1]
	v_pk_add_f32 v[12:13], v[12:13], v[218:219] neg_lo:[0,1] neg_hi:[0,1]
	v_pk_add_f32 v[14:15], v[14:15], v[218:219] neg_lo:[0,1] neg_hi:[0,1]
	v_exp_f32_e32 v0, v0
	v_exp_f32_e32 v1, v1
	v_exp_f32_e32 v2, v2
	v_exp_f32_e32 v3, v3
	v_exp_f32_e32 v4, v4
	v_exp_f32_e32 v5, v5
	v_exp_f32_e32 v6, v6
	v_exp_f32_e32 v7, v7
	v_exp_f32_e32 v8, v8
	v_exp_f32_e32 v9, v9
	v_exp_f32_e32 v10, v10
	v_exp_f32_e32 v11, v11
	v_exp_f32_e32 v12, v12
	v_exp_f32_e32 v13, v13
	v_exp_f32_e32 v14, v14
	v_exp_f32_e32 v15, v15
	ds_read_b128 v[112:115], v226 offset:32768
	ds_read_b128 v[116:119], v226 offset:36864
	ds_read_b128 v[120:123], v226 offset:40960
	ds_read_b128 v[124:127], v226 offset:45056
	ds_read_b128 v[128:131], v227 offset:32768
	ds_read_b128 v[132:135], v227 offset:36864
	ds_read_b128 v[136:139], v227 offset:40960
	ds_read_b128 v[140:143], v227 offset:45056
	v_mov_b32_e32 v221, v220
	v_pk_add_f32 v[222:223], v[0:1], v[2:3]
	v_pk_add_f32 v[222:223], v[222:223], v[4:5]
	v_pk_add_f32 v[222:223], v[222:223], v[6:7]
	v_pk_add_f32 v[222:223], v[222:223], v[8:9]
	v_pk_add_f32 v[222:223], v[222:223], v[10:11]
	v_pk_add_f32 v[222:223], v[222:223], v[12:13]
	v_pk_add_f32 v[222:223], v[222:223], v[14:15]
	v_pk_mul_f32 v[32:33], v[32:33], v[220:221]
	v_pk_mul_f32 v[34:35], v[34:35], v[220:221]
	v_pk_mul_f32 v[36:37], v[36:37], v[220:221]
	v_pk_mul_f32 v[38:39], v[38:39], v[220:221]
	v_pk_mul_f32 v[40:41], v[40:41], v[220:221]
	v_pk_mul_f32 v[42:43], v[42:43], v[220:221]
	v_pk_mul_f32 v[44:45], v[44:45], v[220:221]
	v_pk_mul_f32 v[46:47], v[46:47], v[220:221]
	v_add_f32_e32 v203, v222, v223
	v_fma_f32 v201, v201, v220, v203
	v_cvt_pk_bf16_f32 v48, v0, v1
	v_cvt_pk_bf16_f32 v49, v2, v3
	v_cvt_pk_bf16_f32 v50, v4, v5
	v_cvt_pk_bf16_f32 v51, v6, v7
	v_cvt_pk_bf16_f32 v52, v8, v9
	v_cvt_pk_bf16_f32 v53, v10, v11
	v_cvt_pk_bf16_f32 v54, v12, v13
	v_cvt_pk_bf16_f32 v55, v14, v15
	s_waitcnt lgkmcnt(7)
	v_mfma_f32_16x16x32_bf16 v[32:35], v[112:115], v[48:51], v[32:35]
	s_waitcnt lgkmcnt(6)
	v_mfma_f32_16x16x32_bf16 v[36:39], v[116:119], v[48:51], v[36:39]
	s_waitcnt lgkmcnt(5)
	v_mfma_f32_16x16x32_bf16 v[40:43], v[120:123], v[48:51], v[40:43]
	s_waitcnt lgkmcnt(4)
	v_mfma_f32_16x16x32_bf16 v[44:47], v[124:127], v[48:51], v[44:47]
	s_waitcnt lgkmcnt(3)
	v_mfma_f32_16x16x32_bf16 v[32:35], v[128:131], v[52:55], v[32:35]
	s_waitcnt lgkmcnt(2)
	v_mfma_f32_16x16x32_bf16 v[36:39], v[132:135], v[52:55], v[36:39]
	s_waitcnt lgkmcnt(1)
	v_mfma_f32_16x16x32_bf16 v[40:43], v[136:139], v[52:55], v[40:43]
	s_waitcnt lgkmcnt(0)
	v_mfma_f32_16x16x32_bf16 v[44:47], v[140:143], v[52:55], v[44:47]
	ds_read_b32 v0, v184 offset:896
	ds_read_b32 v1, v185 offset:896
	ds_read_b32 v2, v186 offset:896
	ds_read_b32 v3, v187 offset:896
	ds_read_b32 v4, v188 offset:896
	ds_read_b32 v5, v189 offset:896
	ds_read_b32 v6, v190 offset:896
	ds_read_b32 v7, v191 offset:896
	ds_read_b32 v8, v184 offset:1024
	ds_read_b32 v9, v185 offset:1024
	ds_read_b32 v10, v186 offset:1024
	ds_read_b32 v11, v187 offset:1024
	ds_read_b32 v12, v188 offset:1024
	ds_read_b32 v13, v189 offset:1024
	ds_read_b32 v14, v190 offset:1024
	ds_read_b32 v15, v191 offset:1024
	s_waitcnt vmcnt(0)
	s_waitcnt lgkmcnt(0)
	s_barrier
; __device__ __forceinline__ void attn_phase(const Params& P, char* smem_raw) {
;     ...
;       __syncthreads();
;       f32x4 sacc[8];
; #pragma unroll
;       for (int t8 = 0; t8 < 8; ++t8) sacc[t8] = f32x4{0.f, 0.f, 0.f, 0.f};
; #pragma unroll
;       for (int s = 0; s < 2; ++s)
; #pragma unroll
;         for (int t8 = 0; t8 < 8; ++t8) {
;           const bf16x8 kf = *reinterpret_cast<const bf16x8*>(&sm_k[(t8 * 16 + (lane_c & 15)) * LDSS + s * 32 + (lane_c >> 4) * 8]);
;           sacc[t8] = __builtin_amdgcn_mfma_f32_16x16x32_bf16(qf[s], kf, sacc[t8], 0, 0, 0);
;         }
;       if (ck < 5) {
;         ATT_ISSUE(t, ck + 1)
;       } else if (t + VGRID < 8192) {
;         ATT_ISSUE(t + VGRID, 0)
;         ATT_QLOAD(t + VGRID)
;       }
;       if (ck < 4) {
;         const float* rb0 = sm_rpb + (rs + ck * 2 - r + 7) * 31;
; #pragma unroll
;         for (int t8 = 0; t8 < 8; ++t8)
; #pragma unroll
;           for (int reg = 0; reg < 4; ++reg)
;             sacc[t8][reg] += rb0[(t8 >> 2) * 31 + dco[reg][t8 & 3]];
;       }
; #pragma unroll
;       for (int reg = 0; reg < 4; ++reg) {
;         float mx = sacc[0][reg];
; #pragma unroll
;         for (int t8 = 1; t8 < 8; ++t8) mx = fmaxf(mx, sacc[t8][reg]);
;         mx = row16_max(mx);
;         const float mnew = fmaxf(mrow[reg], mx);
;         const float alpha = __builtin_amdgcn_exp2f(mrow[reg] - mnew);
;         mrow[reg] = mnew;
;         float rsum = 0.f;
; #pragma unroll
;         for (int t8 = 0; t8 < 8; ++t8) {
;           const float p = __builtin_amdgcn_exp2f(sacc[t8][reg] - mnew);
;           rsum += p;
;           sm_p[(wid * 16 + (lane_c >> 4) * 4 + reg) * 136 + t8 * 16 + (lane_c & 15)] = f2bf(p);
;         }
;         rsum = row16_sum(rsum);
;         lrow[reg] = lrow[reg] * alpha + rsum;
; #pragma unroll
;         for (int td = 0; td < 4; ++td) o[td][reg] *= alpha;
;       }
;       asm volatile("s_waitcnt lgkmcnt(0)" ::: "memory");
; #pragma unroll
;       for (int s4 = 0; s4 < 4; ++s4) {
;         const bf16x8 pf = *reinterpret_cast<const bf16x8*>(&sm_p[(wid * 16 + (lane_c & 15)) * 136 + s4 * 32 + (lane_c >> 4) * 8]);
; #pragma unroll
;         for (int td = 0; td < 4; ++td) {
;           const bf16x8 vf = *reinterpret_cast<const bf16x8*>(&sm_vt[(td * 16 + (lane_c & 15)) * 136 + s4 * 32 + (lane_c >> 4) * 8]);
;           o[td] = __builtin_amdgcn_mfma_f32_16x16x32_bf16(pf, vf, o[td], 0, 0, 0);
	s_add_u32 s100, s12, 0x240800
	s_addc_u32 s101, s13, 0
	s_add_u32 s0, s14, 0x300
	s_addc_u32 s1, s15, 0
	s_add_u32 m0, s18, 0x8000
	s_nop 0
	v_mad_u64_u32 v[230:231], vcc, v154, 1, s[100:101]
	global_load_lds_dwordx4 v[230:231], off
	s_add_u32 m0, s18, 0xc000
	s_nop 0
	v_mad_u64_u32 v[232:233], vcc, v158, 1, s[0:1]
	global_load_lds_dwordx4 v[232:233], off
	s_add_u32 m0, s18, 0x8400
	s_nop 0
	v_mad_u64_u32 v[230:231], vcc, v155, 1, s[100:101]
	global_load_lds_dwordx4 v[230:231], off
	s_add_u32 m0, s18, 0xc400
	s_nop 0
	v_mad_u64_u32 v[232:233], vcc, v159, 1, s[0:1]
	global_load_lds_dwordx4 v[232:233], off
	s_add_u32 m0, s18, 0x8800
	s_nop 0
	v_mad_u64_u32 v[230:231], vcc, v156, 1, s[100:101]
	global_load_lds_dwordx4 v[230:231], off
	s_add_u32 m0, s18, 0xc800
	s_nop 0
	v_mad_u64_u32 v[232:233], vcc, v160, 1, s[0:1]
	global_load_lds_dwordx4 v[232:233], off
	s_add_u32 m0, s18, 0x8c00
	s_nop 0
	v_mad_u64_u32 v[230:231], vcc, v157, 1, s[100:101]
	global_load_lds_dwordx4 v[230:231], off
	s_add_u32 m0, s18, 0xcc00
	s_nop 0
	v_mad_u64_u32 v[232:233], vcc, v161, 1, s[0:1]
	global_load_lds_dwordx4 v[232:233], off
	ds_read_b128 v[112:115], v224 offset:0
	ds_read_b128 v[116:119], v225 offset:0
	ds_read_b128 v[120:123], v224 offset:512
	ds_read_b128 v[124:127], v225 offset:512
	ds_read_b128 v[128:131], v224 offset:8192
	ds_read_b128 v[132:135], v225 offset:8192
	ds_read_b128 v[136:139], v224 offset:8704
	ds_read_b128 v[140:143], v225 offset:8704
	s_waitcnt lgkmcnt(7)
	v_mfma_f32_16x16x32_bf16 v[0:3], v[112:115], v[64:67], v[0:3]
	s_waitcnt lgkmcnt(6)
	v_mfma_f32_16x16x32_bf16 v[0:3], v[116:119], v[68:71], v[0:3]
	s_waitcnt lgkmcnt(5)
	v_mfma_f32_16x16x32_bf16 v[4:7], v[120:123], v[64:67], v[4:7]
	s_waitcnt lgkmcnt(4)
	v_mfma_f32_16x16x32_bf16 v[4:7], v[124:127], v[68:71], v[4:7]
	s_waitcnt lgkmcnt(3)
	v_mfma_f32_16x16x32_bf16 v[8:11], v[128:131], v[64:67], v[8:11]
	s_waitcnt lgkmcnt(2)
	v_mfma_f32_16x16x32_bf16 v[8:11], v[132:135], v[68:71], v[8:11]
	s_waitcnt lgkmcnt(1)
	v_mfma_f32_16x16x32_bf16 v[12:15], v[136:139], v[64:67], v[12:15]
	s_waitcnt lgkmcnt(0)
	v_mfma_f32_16x16x32_bf16 v[12:15], v[140:143], v[68:71], v[12:15]
	s_nop 7
	v_max3_f32 v203, v0, v1, v2
	v_max3_f32 v203, v203, v3, v4
	v_max3_f32 v203, v203, v5, v6
	v_max3_f32 v203, v203, v7, v8
	v_max3_f32 v203, v203, v9, v10
	v_max3_f32 v203, v203, v11, v12
	v_max3_f32 v203, v203, v13, v14
	v_max_f32_e32 v203, v203, v15
	v_mov_b32_e32 v205, v203
	s_nop 1
	v_permlane16_swap_b32_e32 v203, v205
	v_max_f32_e32 v203, v203, v205
	v_mov_b32_e32 v205, v203
	s_nop 1
	v_permlane32_swap_b32_e32 v203, v205
	v_max_f32_e32 v203, v203, v205
	v_max_f32_e32 v218, v200, v203
	v_sub_f32_e32 v220, v200, v218
	v_mov_b32_e32 v219, v218
	v_exp_f32_e32 v220, v220
	v_mov_b32_e32 v200, v218
	v_pk_add_f32 v[0:1], v[0:1], v[218:219] neg_lo:[0,1] neg_hi:[0,1]
	v_pk_add_f32 v[2:3], v[2:3], v[218:219] neg_lo:[0,1] neg_hi:[0,1]
	v_pk_add_f32 v[4:5], v[4:5], v[218:219] neg_lo:[0,1] neg_hi:[0,1]
	v_pk_add_f32 v[6:7], v[6:7], v[218:219] neg_lo:[0,1] neg_hi:[0,1]
	v_pk_add_f32 v[8:9], v[8:9], v[218:219] neg_lo:[0,1] neg_hi:[0,1]
	v_pk_add_f32 v[10:11], v[10:11], v[218:219] neg_lo:[0,1] neg_hi:[0,1]
	v_pk_add_f32 v[12:13], v[12:13], v[218:219] neg_lo:[0,1] neg_hi:[0,1]
	v_pk_add_f32 v[14:15], v[14:15], v[218:219] neg_lo:[0,1] neg_hi:[0,1]
	v_exp_f32_e32 v0, v0
	v_exp_f32_e32 v1, v1
	v_exp_f32_e32 v2, v2
	v_exp_f32_e32 v3, v3
	v_exp_f32_e32 v4, v4
	v_exp_f32_e32 v5, v5
	v_exp_f32_e32 v6, v6
	v_exp_f32_e32 v7, v7
	v_exp_f32_e32 v8, v8
	v_exp_f32_e32 v9, v9
	v_exp_f32_e32 v10, v10
	v_exp_f32_e32 v11, v11
	v_exp_f32_e32 v12, v12
	v_exp_f32_e32 v13, v13
	v_exp_f32_e32 v14, v14
	v_exp_f32_e32 v15, v15
	ds_read_b128 v[112:115], v226 offset:0
	ds_read_b128 v[116:119], v226 offset:4096
	ds_read_b128 v[120:123], v226 offset:8192
	ds_read_b128 v[124:127], v226 offset:12288
	ds_read_b128 v[128:131], v227 offset:0
	ds_read_b128 v[132:135], v227 offset:4096
	ds_read_b128 v[136:139], v227 offset:8192
	ds_read_b128 v[140:143], v227 offset:12288
	v_mov_b32_e32 v221, v220
	v_pk_add_f32 v[222:223], v[0:1], v[2:3]
	v_pk_add_f32 v[222:223], v[222:223], v[4:5]
	v_pk_add_f32 v[222:223], v[222:223], v[6:7]
	v_pk_add_f32 v[222:223], v[222:223], v[8:9]
	v_pk_add_f32 v[222:223], v[222:223], v[10:11]
	v_pk_add_f32 v[222:223], v[222:223], v[12:13]
	v_pk_add_f32 v[222:223], v[222:223], v[14:15]
	v_pk_mul_f32 v[32:33], v[32:33], v[220:221]
	v_pk_mul_f32 v[34:35], v[34:35], v[220:221]
	v_pk_mul_f32 v[36:37], v[36:37], v[220:221]
	v_pk_mul_f32 v[38:39], v[38:39], v[220:221]
	v_pk_mul_f32 v[40:41], v[40:41], v[220:221]
	v_pk_mul_f32 v[42:43], v[42:43], v[220:221]
	v_pk_mul_f32 v[44:45], v[44:45], v[220:221]
	v_pk_mul_f32 v[46:47], v[46:47], v[220:221]
	v_add_f32_e32 v203, v222, v223
	v_fma_f32 v201, v201, v220, v203
	v_cvt_pk_bf16_f32 v48, v0, v1
	v_cvt_pk_bf16_f32 v49, v2, v3
	v_cvt_pk_bf16_f32 v50, v4, v5
	v_cvt_pk_bf16_f32 v51, v6, v7
	v_cvt_pk_bf16_f32 v52, v8, v9
	v_cvt_pk_bf16_f32 v53, v10, v11
	v_cvt_pk_bf16_f32 v54, v12, v13
	v_cvt_pk_bf16_f32 v55, v14, v15
	s_waitcnt lgkmcnt(7)
	v_mfma_f32_16x16x32_bf16 v[32:35], v[112:115], v[48:51], v[32:35]
	s_waitcnt lgkmcnt(6)
	v_mfma_f32_16x16x32_bf16 v[36:39], v[116:119], v[48:51], v[36:39]
	s_waitcnt lgkmcnt(5)
	v_mfma_f32_16x16x32_bf16 v[40:43], v[120:123], v[48:51], v[40:43]
	s_waitcnt lgkmcnt(4)
	v_mfma_f32_16x16x32_bf16 v[44:47], v[124:127], v[48:51], v[44:47]
	s_waitcnt lgkmcnt(3)
	v_mfma_f32_16x16x32_bf16 v[32:35], v[128:131], v[52:55], v[32:35]
	s_waitcnt lgkmcnt(2)
	v_mfma_f32_16x16x32_bf16 v[36:39], v[132:135], v[52:55], v[36:39]
	s_waitcnt lgkmcnt(1)
	v_mfma_f32_16x16x32_bf16 v[40:43], v[136:139], v[52:55], v[40:43]
	s_waitcnt lgkmcnt(0)
	v_mfma_f32_16x16x32_bf16 v[44:47], v[140:143], v[52:55], v[44:47]
	ds_read_b32 v0, v184 offset:1152
	ds_read_b32 v1, v185 offset:1152
	ds_read_b32 v2, v186 offset:1152
	ds_read_b32 v3, v187 offset:1152
	ds_read_b32 v4, v188 offset:1152
	ds_read_b32 v5, v189 offset:1152
	ds_read_b32 v6, v190 offset:1152
	ds_read_b32 v7, v191 offset:1152
	ds_read_b32 v8, v184 offset:1280
	ds_read_b32 v9, v185 offset:1280
	ds_read_b32 v10, v186 offset:1280
	ds_read_b32 v11, v187 offset:1280
	ds_read_b32 v12, v188 offset:1280
	ds_read_b32 v13, v189 offset:1280
	ds_read_b32 v14, v190 offset:1280
	ds_read_b32 v15, v191 offset:1280
	s_waitcnt vmcnt(0)
	s_waitcnt lgkmcnt(0)
	s_barrier
; __device__ __forceinline__ void attn_phase(const Params& P, char* smem_raw) {
;     ...
;       __syncthreads();
;       f32x4 sacc[8];
; #pragma unroll
;       for (int t8 = 0; t8 < 8; ++t8) sacc[t8] = f32x4{0.f, 0.f, 0.f, 0.f};
; #pragma unroll
;       for (int s = 0; s < 2; ++s)
; #pragma unroll
;         for (int t8 = 0; t8 < 8; ++t8) {
;           const bf16x8 kf = *reinterpret_cast<const bf16x8*>(&sm_k[(t8 * 16 + (lane_c & 15)) * LDSS + s * 32 + (lane_c >> 4) * 8]);
;           sacc[t8] = __builtin_amdgcn_mfma_f32_16x16x32_bf16(qf[s], kf, sacc[t8], 0, 0, 0);
;         }
;       if (ck < 5) {
;         ATT_ISSUE(t, ck + 1)
;       } else if (t + VGRID < 8192) {
;         ATT_ISSUE(t + VGRID, 0)
;         ATT_QLOAD(t + VGRID)
;       }
;       if (ck < 4) {
;         const float* rb0 = sm_rpb + (rs + ck * 2 - r + 7) * 31;
; #pragma unroll
;         for (int t8 = 0; t8 < 8; ++t8)
; #pragma unroll
;           for (int reg = 0; reg < 4; ++reg)
;             sacc[t8][reg] += rb0[(t8 >> 2) * 31 + dco[reg][t8 & 3]];
;       }
; #pragma unroll
;       for (int reg = 0; reg < 4; ++reg) {
;         float mx = sacc[0][reg];
; #pragma unroll
;         for (int t8 = 1; t8 < 8; ++t8) mx = fmaxf(mx, sacc[t8][reg]);
;         mx = row16_max(mx);
;         const float mnew = fmaxf(mrow[reg], mx);
;         const float alpha = __builtin_amdgcn_exp2f(mrow[reg] - mnew);
;         mrow[reg] = mnew;
;         float rsum = 0.f;
; #pragma unroll
;         for (int t8 = 0; t8 < 8; ++t8) {
;           const float p = __builtin_amdgcn_exp2f(sacc[t8][reg] - mnew);
;           rsum += p;
;           sm_p[(wid * 16 + (lane_c >> 4) * 4 + reg) * 136 + t8 * 16 + (lane_c & 15)] = f2bf(p);
;         }
;         rsum = row16_sum(rsum);
;         lrow[reg] = lrow[reg] * alpha + rsum;
; #pragma unroll
;         for (int td = 0; td < 4; ++td) o[td][reg] *= alpha;
;       }
;       asm volatile("s_waitcnt lgkmcnt(0)" ::: "memory");
; #pragma unroll
;       for (int s4 = 0; s4 < 4; ++s4) {
;         const bf16x8 pf = *reinterpret_cast<const bf16x8*>(&sm_p[(wid * 16 + (lane_c & 15)) * 136 + s4 * 32 + (lane_c >> 4) * 8]);
; #pragma unroll
;         for (int td = 0; td < 4; ++td) {
;           const bf16x8 vf = *reinterpret_cast<const bf16x8*>(&sm_vt[(td * 16 + (lane_c & 15)) * 136 + s4 * 32 + (lane_c >> 4) * 8]);
;           o[td] = __builtin_amdgcn_mfma_f32_16x16x32_bf16(pf, vf, o[td], 0, 0, 0);
	s_add_u32 s100, s16, 0x800
	s_addc_u32 s101, s17, 0
	s_add_u32 s0, s36, 0x0
	s_addc_u32 s1, s37, 0
	s_add_u32 m0, s18, 0x0
	s_nop 0
	v_mad_u64_u32 v[230:231], vcc, v154, 1, s[100:101]
	global_load_lds_dwordx4 v[230:231], off
	s_add_u32 m0, s18, 0x4000
	s_nop 0
	v_mad_u64_u32 v[232:233], vcc, v162, 1, s[0:1]
	global_load_lds_dwordx4 v[232:233], off
	s_add_u32 m0, s18, 0x400
	s_nop 0
	v_mad_u64_u32 v[230:231], vcc, v155, 1, s[100:101]
	global_load_lds_dwordx4 v[230:231], off
	s_add_u32 m0, s18, 0x4400
	s_nop 0
	v_mad_u64_u32 v[232:233], vcc, v163, 1, s[0:1]
	global_load_lds_dwordx4 v[232:233], off
	s_add_u32 m0, s18, 0x800
	s_nop 0
	v_mad_u64_u32 v[230:231], vcc, v156, 1, s[100:101]
	global_load_lds_dwordx4 v[230:231], off
	s_add_u32 m0, s18, 0x4800
	s_nop 0
	v_mad_u64_u32 v[232:233], vcc, v164, 1, s[0:1]
	global_load_lds_dwordx4 v[232:233], off
	s_add_u32 m0, s18, 0xc00
	s_nop 0
	v_mad_u64_u32 v[230:231], vcc, v157, 1, s[100:101]
	global_load_lds_dwordx4 v[230:231], off
	s_add_u32 m0, s18, 0x4c00
	s_nop 0
	v_mad_u64_u32 v[232:233], vcc, v165, 1, s[0:1]
	global_load_lds_dwordx4 v[232:233], off
	ds_read_b128 v[112:115], v224 offset:32768
	ds_read_b128 v[116:119], v225 offset:32768
	ds_read_b128 v[120:123], v224 offset:33280
	ds_read_b128 v[124:127], v225 offset:33280
	ds_read_b128 v[128:131], v224 offset:40960
	ds_read_b128 v[132:135], v225 offset:40960
	ds_read_b128 v[136:139], v224 offset:41472
	ds_read_b128 v[140:143], v225 offset:41472
	s_waitcnt lgkmcnt(7)
	v_mfma_f32_16x16x32_bf16 v[0:3], v[112:115], v[64:67], v[0:3]
	s_waitcnt lgkmcnt(6)
	v_mfma_f32_16x16x32_bf16 v[0:3], v[116:119], v[68:71], v[0:3]
	s_waitcnt lgkmcnt(5)
	v_mfma_f32_16x16x32_bf16 v[4:7], v[120:123], v[64:67], v[4:7]
	s_waitcnt lgkmcnt(4)
	v_mfma_f32_16x16x32_bf16 v[4:7], v[124:127], v[68:71], v[4:7]
	s_waitcnt lgkmcnt(3)
	v_mfma_f32_16x16x32_bf16 v[8:11], v[128:131], v[64:67], v[8:11]
	s_waitcnt lgkmcnt(2)
	v_mfma_f32_16x16x32_bf16 v[8:11], v[132:135], v[68:71], v[8:11]
	s_waitcnt lgkmcnt(1)
	v_mfma_f32_16x16x32_bf16 v[12:15], v[136:139], v[64:67], v[12:15]
	s_waitcnt lgkmcnt(0)
	v_mfma_f32_16x16x32_bf16 v[12:15], v[140:143], v[68:71], v[12:15]
	s_nop 7
	v_max3_f32 v203, v0, v1, v2
	v_max3_f32 v203, v203, v3, v4
	v_max3_f32 v203, v203, v5, v6
	v_max3_f32 v203, v203, v7, v8
	v_max3_f32 v203, v203, v9, v10
	v_max3_f32 v203, v203, v11, v12
	v_max3_f32 v203, v203, v13, v14
	v_max_f32_e32 v203, v203, v15
	v_mov_b32_e32 v205, v203
	s_nop 1
	v_permlane16_swap_b32_e32 v203, v205
	v_max_f32_e32 v203, v203, v205
	v_mov_b32_e32 v205, v203
	s_nop 1
	v_permlane32_swap_b32_e32 v203, v205
	v_max_f32_e32 v203, v203, v205
	v_max_f32_e32 v218, v200, v203
	v_sub_f32_e32 v220, v200, v218
	v_mov_b32_e32 v219, v218
	v_exp_f32_e32 v220, v220
	v_mov_b32_e32 v200, v218
	v_pk_add_f32 v[0:1], v[0:1], v[218:219] neg_lo:[0,1] neg_hi:[0,1]
	v_pk_add_f32 v[2:3], v[2:3], v[218:219] neg_lo:[0,1] neg_hi:[0,1]
	v_pk_add_f32 v[4:5], v[4:5], v[218:219] neg_lo:[0,1] neg_hi:[0,1]
	v_pk_add_f32 v[6:7], v[6:7], v[218:219] neg_lo:[0,1] neg_hi:[0,1]
	v_pk_add_f32 v[8:9], v[8:9], v[218:219] neg_lo:[0,1] neg_hi:[0,1]
	v_pk_add_f32 v[10:11], v[10:11], v[218:219] neg_lo:[0,1] neg_hi:[0,1]
	v_pk_add_f32 v[12:13], v[12:13], v[218:219] neg_lo:[0,1] neg_hi:[0,1]
	v_pk_add_f32 v[14:15], v[14:15], v[218:219] neg_lo:[0,1] neg_hi:[0,1]
	v_exp_f32_e32 v0, v0
	v_exp_f32_e32 v1, v1
	v_exp_f32_e32 v2, v2
	v_exp_f32_e32 v3, v3
	v_exp_f32_e32 v4, v4
	v_exp_f32_e32 v5, v5
	v_exp_f32_e32 v6, v6
	v_exp_f32_e32 v7, v7
	v_exp_f32_e32 v8, v8
	v_exp_f32_e32 v9, v9
	v_exp_f32_e32 v10, v10
	v_exp_f32_e32 v11, v11
	v_exp_f32_e32 v12, v12
	v_exp_f32_e32 v13, v13
	v_exp_f32_e32 v14, v14
	v_exp_f32_e32 v15, v15
	s_and_b32 s0, s3, 0xff
	s_add_u32 s0, s0, 1
	s_min_u32 s0, s0, 15
	s_lshr_b32 s1, s0, 2
	s_and_b32 s0, s0, 3
	s_lshl_b32 s0, s0, 5
	s_lshr_b32 vcc_lo, s3, 12
	s_add_u32 s0, s0, vcc_lo
	s_sub_i32 vcc_lo, s0, 4
	s_max_i32 vcc_lo, vcc_lo, 0
	s_min_i32 vcc_lo, vcc_lo, 0x78
	s_lshl_b32 vcc_hi, s1, 13
	s_lshl_b32 m0, vcc_lo, 6
	s_add_u32 m0, m0, vcc_hi
	s_mul_i32 m0, m0, 0x1800
	s_add_u32 s12, s4, m0
	s_addc_u32 s13, s5, 0
	s_lshl_b32 m0, s1, 24
	s_lshl_b32 s100, vcc_lo, 7
	s_add_u32 m0, m0, s100
	s_add_u32 s14, s6, m0
	s_addc_u32 s15, s7, 0
	s_lshl_b32 m0, s0, 6
	s_add_u32 m0, m0, vcc_hi
	s_mul_i32 m0, m0, 0x1800
	s_add_u32 s100, s4, m0
	s_addc_u32 s101, s5, 0
	global_load_dwordx4 v[72:75], v166, s[100:101]
	global_load_dwordx4 v[76:79], v166, s[100:101] offset:64
	ds_read_b128 v[112:115], v226 offset:32768
	ds_read_b128 v[116:119], v226 offset:36864
	ds_read_b128 v[120:123], v226 offset:40960
	ds_read_b128 v[124:127], v226 offset:45056
	ds_read_b128 v[128:131], v227 offset:32768
	ds_read_b128 v[132:135], v227 offset:36864
	ds_read_b128 v[136:139], v227 offset:40960
	ds_read_b128 v[140:143], v227 offset:45056
	v_mov_b32_e32 v221, v220
	v_pk_add_f32 v[222:223], v[0:1], v[2:3]
	v_pk_add_f32 v[222:223], v[222:223], v[4:5]
	v_pk_add_f32 v[222:223], v[222:223], v[6:7]
	v_pk_add_f32 v[222:223], v[222:223], v[8:9]
	v_pk_add_f32 v[222:223], v[222:223], v[10:11]
	v_pk_add_f32 v[222:223], v[222:223], v[12:13]
	v_pk_add_f32 v[222:223], v[222:223], v[14:15]
	v_pk_mul_f32 v[32:33], v[32:33], v[220:221]
	v_pk_mul_f32 v[34:35], v[34:35], v[220:221]
	v_pk_mul_f32 v[36:37], v[36:37], v[220:221]
	v_pk_mul_f32 v[38:39], v[38:39], v[220:221]
	v_pk_mul_f32 v[40:41], v[40:41], v[220:221]
	v_pk_mul_f32 v[42:43], v[42:43], v[220:221]
	v_pk_mul_f32 v[44:45], v[44:45], v[220:221]
	v_pk_mul_f32 v[46:47], v[46:47], v[220:221]
	v_add_f32_e32 v203, v222, v223
	v_fma_f32 v201, v201, v220, v203
	v_cvt_pk_bf16_f32 v48, v0, v1
	v_cvt_pk_bf16_f32 v49, v2, v3
	v_cvt_pk_bf16_f32 v50, v4, v5
	v_cvt_pk_bf16_f32 v51, v6, v7
	v_cvt_pk_bf16_f32 v52, v8, v9
	v_cvt_pk_bf16_f32 v53, v10, v11
	v_cvt_pk_bf16_f32 v54, v12, v13
	v_cvt_pk_bf16_f32 v55, v14, v15
	s_waitcnt lgkmcnt(7)
	v_mfma_f32_16x16x32_bf16 v[32:35], v[112:115], v[48:51], v[32:35]
	s_waitcnt lgkmcnt(6)
	v_mfma_f32_16x16x32_bf16 v[36:39], v[116:119], v[48:51], v[36:39]
	s_waitcnt lgkmcnt(5)
	v_mfma_f32_16x16x32_bf16 v[40:43], v[120:123], v[48:51], v[40:43]
	s_waitcnt lgkmcnt(4)
	v_mfma_f32_16x16x32_bf16 v[44:47], v[124:127], v[48:51], v[44:47]
	s_waitcnt lgkmcnt(3)
	v_mfma_f32_16x16x32_bf16 v[32:35], v[128:131], v[52:55], v[32:35]
	s_waitcnt lgkmcnt(2)
	v_mfma_f32_16x16x32_bf16 v[36:39], v[132:135], v[52:55], v[36:39]
	s_waitcnt lgkmcnt(1)
	v_mfma_f32_16x16x32_bf16 v[40:43], v[136:139], v[52:55], v[40:43]
	s_waitcnt lgkmcnt(0)
	v_mfma_f32_16x16x32_bf16 v[44:47], v[140:143], v[52:55], v[44:47]
	s_waitcnt vmcnt(2)
	s_waitcnt lgkmcnt(0)
	s_barrier
; __device__ __forceinline__ void attn_phase(const Params& P, char* smem_raw) {
;     ...
;       __syncthreads();
;       f32x4 sacc[8];
; #pragma unroll
;       for (int t8 = 0; t8 < 8; ++t8) sacc[t8] = f32x4{0.f, 0.f, 0.f, 0.f};
; #pragma unroll
;       for (int s = 0; s < 2; ++s)
; #pragma unroll
;         for (int t8 = 0; t8 < 8; ++t8) {
;           const bf16x8 kf = *reinterpret_cast<const bf16x8*>(&sm_k[(t8 * 16 + (lane_c & 15)) * LDSS + s * 32 + (lane_c >> 4) * 8]);
;           sacc[t8] = __builtin_amdgcn_mfma_f32_16x16x32_bf16(qf[s], kf, sacc[t8], 0, 0, 0);
;         }
;       if (ck < 5) {
;         ATT_ISSUE(t, ck + 1)
;       } else if (t + VGRID < 8192) {
;         ATT_ISSUE(t + VGRID, 0)
;         ATT_QLOAD(t + VGRID)
;       }
;       if (ck < 4) {
;         const float* rb0 = sm_rpb + (rs + ck * 2 - r + 7) * 31;
; #pragma unroll
;         for (int t8 = 0; t8 < 8; ++t8)
; #pragma unroll
;           for (int reg = 0; reg < 4; ++reg)
;             sacc[t8][reg] += rb0[(t8 >> 2) * 31 + dco[reg][t8 & 3]];
;       }
; #pragma unroll
;       for (int reg = 0; reg < 4; ++reg) {
;         float mx = sacc[0][reg];
; #pragma unroll
;         for (int t8 = 1; t8 < 8; ++t8) mx = fmaxf(mx, sacc[t8][reg]);
;         mx = row16_max(mx);
	s_add_u32 s100, s16, 0xc0800
	s_addc_u32 s101, s17, 0
	s_add_u32 s0, s36, 0x100
	s_addc_u32 s1, s37, 0
	s_add_u32 m0, s18, 0x8000
	s_nop 0
	v_mad_u64_u32 v[230:231], vcc, v154, 1, s[100:101]
	global_load_lds_dwordx4 v[230:231], off
	s_add_u32 m0, s18, 0xc000
	s_nop 0
	v_mad_u64_u32 v[232:233], vcc, v162, 1, s[0:1]
	global_load_lds_dwordx4 v[232:233], off
	s_add_u32 m0, s18, 0x8400
	s_nop 0
	v_mad_u64_u32 v[230:231], vcc, v155, 1, s[100:101]
	global_load_lds_dwordx4 v[230:231], off
	s_add_u32 m0, s18, 0xc400
	s_nop 0
	v_mad_u64_u32 v[232:233], vcc, v163, 1, s[0:1]
	global_load_lds_dwordx4 v[232:233], off
	s_add_u32 m0, s18, 0x8800
	s_nop 0
	v_mad_u64_u32 v[230:231], vcc, v156, 1, s[100:101]
	global_load_lds_dwordx4 v[230:231], off
	s_add_u32 m0, s18, 0xc800
	s_nop 0
	v_mad_u64_u32 v[232:233], vcc, v164, 1, s[0:1]
	global_load_lds_dwordx4 v[232:233], off
	s_add_u32 m0, s18, 0x8c00
	s_nop 0
	v_mad_u64_u32 v[230:231], vcc, v157, 1, s[100:101]
	global_load_lds_dwordx4 v[230:231], off
	s_add_u32 m0, s18, 0xcc00
	s_nop 0
	v_mad_u64_u32 v[232:233], vcc, v165, 1, s[0:1]
	global_load_lds_dwordx4 v[232:233], off
	ds_read_b128 v[112:115], v144 offset:0
	ds_read_b128 v[116:119], v145 offset:0
	ds_read_b128 v[120:123], v144 offset:512
	ds_read_b128 v[124:127], v145 offset:512
	ds_read_b128 v[128:131], v144 offset:4096
	ds_read_b128 v[132:135], v145 offset:4096
	ds_read_b128 v[136:139], v144 offset:4608
	ds_read_b128 v[140:143], v145 offset:4608
	s_waitcnt lgkmcnt(7)
	v_mfma_f32_16x16x32_bf16 v[0:3], v[112:115], v[64:67], 0
	ds_read_b128 v[112:115], v144 offset:8192
	s_waitcnt lgkmcnt(7)
	v_mfma_f32_16x16x32_bf16 v[0:3], v[116:119], v[68:71], v[0:3]
	ds_read_b128 v[116:119], v145 offset:8192
	s_waitcnt lgkmcnt(7)
	v_mfma_f32_16x16x32_bf16 v[4:7], v[120:123], v[64:67], 0
	ds_read_b128 v[120:123], v144 offset:8704
	s_waitcnt lgkmcnt(7)
	v_mfma_f32_16x16x32_bf16 v[4:7], v[124:127], v[68:71], v[4:7]
	ds_read_b128 v[124:127], v145 offset:8704
	s_waitcnt lgkmcnt(7)
	v_mfma_f32_16x16x32_bf16 v[8:11], v[128:131], v[64:67], 0
	ds_read_b128 v[128:131], v144 offset:12288
	s_waitcnt lgkmcnt(7)
	v_mfma_f32_16x16x32_bf16 v[8:11], v[132:135], v[68:71], v[8:11]
	ds_read_b128 v[132:135], v145 offset:12288
	s_waitcnt lgkmcnt(7)
	v_mfma_f32_16x16x32_bf16 v[12:15], v[136:139], v[64:67], 0
	ds_read_b128 v[136:139], v144 offset:12800
	s_waitcnt lgkmcnt(7)
	v_mfma_f32_16x16x32_bf16 v[12:15], v[140:143], v[68:71], v[12:15]
	ds_read_b128 v[140:143], v145 offset:12800
	s_waitcnt lgkmcnt(7)
	v_mfma_f32_16x16x32_bf16 v[16:19], v[112:115], v[64:67], 0
	s_waitcnt lgkmcnt(6)
	v_mfma_f32_16x16x32_bf16 v[16:19], v[116:119], v[68:71], v[16:19]
	s_waitcnt lgkmcnt(5)
	v_mfma_f32_16x16x32_bf16 v[20:23], v[120:123], v[64:67], 0
	s_waitcnt lgkmcnt(4)
	v_mfma_f32_16x16x32_bf16 v[20:23], v[124:127], v[68:71], v[20:23]
	s_waitcnt lgkmcnt(3)
	v_mfma_f32_16x16x32_bf16 v[24:27], v[128:131], v[64:67], 0
	s_waitcnt lgkmcnt(2)
	v_mfma_f32_16x16x32_bf16 v[24:27], v[132:135], v[68:71], v[24:27]
	s_waitcnt lgkmcnt(1)
	v_mfma_f32_16x16x32_bf16 v[28:31], v[136:139], v[64:67], 0
	s_waitcnt lgkmcnt(0)
	v_mfma_f32_16x16x32_bf16 v[28:31], v[140:143], v[68:71], v[28:31]
	s_nop 7
	v_max3_f32 v203, v0, v1, v2
	v_max3_f32 v203, v203, v3, v4
	v_max3_f32 v203, v203, v5, v6
	v_max3_f32 v203, v203, v7, v8
	v_max3_f32 v203, v203, v9, v10
	v_max3_f32 v203, v203, v11, v12
	v_max3_f32 v203, v203, v13, v14
	v_max3_f32 v203, v203, v15, v16
	v_max3_f32 v203, v203, v17, v18
	v_max3_f32 v203, v203, v19, v20
	v_max3_f32 v203, v203, v21, v22
	v_max3_f32 v203, v203, v23, v24
	v_max3_f32 v203, v203, v25, v26
	v_max3_f32 v203, v203, v27, v28
	v_max3_f32 v203, v203, v29, v30
	v_max_f32_e32 v203, v203, v31
	v_mov_b32_e32 v205, v203
	s_nop 1
	v_permlane16_swap_b32_e32 v203, v205
	v_max_f32_e32 v203, v203, v205
	v_mov_b32_e32 v205, v203
	s_nop 1
	v_permlane32_swap_b32_e32 v203, v205
	v_max_f32_e32 v203, v203, v205
	v_max_f32_e32 v218, v200, v203
	v_sub_f32_e32 v220, v200, v218
	v_mov_b32_e32 v219, v218
	v_exp_f32_e32 v220, v220
	v_mov_b32_e32 v200, v218
	v_pk_add_f32 v[0:1], v[0:1], v[218:219] neg_lo:[0,1] neg_hi:[0,1]
	v_pk_add_f32 v[2:3], v[2:3], v[218:219] neg_lo:[0,1] neg_hi:[0,1]
	v_pk_add_f32 v[4:5], v[4:5], v[218:219] neg_lo:[0,1] neg_hi:[0,1]
	v_pk_add_f32 v[6:7], v[6:7], v[218:219] neg_lo:[0,1] neg_hi:[0,1]
	v_pk_add_f32 v[8:9], v[8:9], v[218:219] neg_lo:[0,1] neg_hi:[0,1]
	v_pk_add_f32 v[10:11], v[10:11], v[218:219] neg_lo:[0,1] neg_hi:[0,1]
	v_pk_add_f32 v[12:13], v[12:13], v[218:219] neg_lo:[0,1] neg_hi:[0,1]
	v_pk_add_f32 v[14:15], v[14:15], v[218:219] neg_lo:[0,1] neg_hi:[0,1]
	v_pk_add_f32 v[16:17], v[16:17], v[218:219] neg_lo:[0,1] neg_hi:[0,1]
	v_pk_add_f32 v[18:19], v[18:19], v[218:219] neg_lo:[0,1] neg_hi:[0,1]
	v_pk_add_f32 v[20:21], v[20:21], v[218:219] neg_lo:[0,1] neg_hi:[0,1]
	v_pk_add_f32 v[22:23], v[22:23], v[218:219] neg_lo:[0,1] neg_hi:[0,1]
	v_pk_add_f32 v[24:25], v[24:25], v[218:219] neg_lo:[0,1] neg_hi:[0,1]
	v_pk_add_f32 v[26:27], v[26:27], v[218:219] neg_lo:[0,1] neg_hi:[0,1]
	v_pk_add_f32 v[28:29], v[28:29], v[218:219] neg_lo:[0,1] neg_hi:[0,1]
	v_pk_add_f32 v[30:31], v[30:31], v[218:219] neg_lo:[0,1] neg_hi:[0,1]
	v_exp_f32_e32 v0, v0
	v_exp_f32_e32 v1, v1
	v_exp_f32_e32 v2, v2
	v_exp_f32_e32 v3, v3
	v_exp_f32_e32 v4, v4
	v_exp_f32_e32 v5, v5
	v_exp_f32_e32 v6, v6
	v_exp_f32_e32 v7, v7
	v_exp_f32_e32 v8, v8
	v_exp_f32_e32 v9, v9
	v_exp_f32_e32 v10, v10
	v_exp_f32_e32 v11, v11
	v_exp_f32_e32 v12, v12
	v_exp_f32_e32 v13, v13
	v_exp_f32_e32 v14, v14
	v_exp_f32_e32 v15, v15
	v_exp_f32_e32 v16, v16
	v_exp_f32_e32 v17, v17
	v_exp_f32_e32 v18, v18
	v_exp_f32_e32 v19, v19
	v_exp_f32_e32 v20, v20
; __device__ __forceinline__ void attn_phase(const Params& P, char* smem_raw) {
;     ...
;         float rsum = 0.f;
; #pragma unroll
;         for (int t8 = 0; t8 < 8; ++t8) {
;           const float p = __builtin_amdgcn_exp2f(sacc[t8][reg] - mnew);
;           rsum += p;
;           sm_p[(wid * 16 + (lane_c >> 4) * 4 + reg) * 136 + t8 * 16 + (lane_c & 15)] = f2bf(p);
;         }
;         rsum = row16_sum(rsum);
;         lrow[reg] = lrow[reg] * alpha + rsum;
; #pragma unroll
;         for (int td = 0; td < 4; ++td) o[td][reg] *= alpha;
;       }
;       asm volatile("s_waitcnt lgkmcnt(0)" ::: "memory");
; #pragma unroll
;       for (int s4 = 0; s4 < 4; ++s4) {
;         const bf16x8 pf = *reinterpret_cast<const bf16x8*>(&sm_p[(wid * 16 + (lane_c & 15)) * 136 + s4 * 32 + (lane_c >> 4) * 8]);
; #pragma unroll
;         for (int td = 0; td < 4; ++td) {
;           const bf16x8 vf = *reinterpret_cast<const bf16x8*>(&sm_vt[(td * 16 + (lane_c & 15)) * 136 + s4 * 32 + (lane_c >> 4) * 8]);
;           o[td] = __builtin_amdgcn_mfma_f32_16x16x32_bf16(pf, vf, o[td], 0, 0, 0);
;         }
;       }
	v_exp_f32_e32 v21, v21
	v_exp_f32_e32 v22, v22
	v_exp_f32_e32 v23, v23
	v_exp_f32_e32 v24, v24
	v_exp_f32_e32 v25, v25
	v_exp_f32_e32 v26, v26
	v_exp_f32_e32 v27, v27
	v_exp_f32_e32 v28, v28
	v_exp_f32_e32 v29, v29
	v_exp_f32_e32 v30, v30
	v_exp_f32_e32 v31, v31
	s_and_b32 s0, s3, 0xff
	s_add_u32 s0, s0, 1
	s_min_u32 s0, s0, 15
	s_lshr_b32 s1, s0, 2
	s_and_b32 s0, s0, 3
	s_lshl_b32 s0, s0, 5
	s_lshr_b32 vcc_lo, s3, 12
	s_add_u32 s0, s0, vcc_lo
	s_sub_i32 vcc_lo, s0, 4
	s_max_i32 vcc_lo, vcc_lo, 0
	s_min_i32 vcc_lo, vcc_lo, 0x78
	s_lshl_b32 vcc_hi, s1, 13
	s_sub_i32 vcc_lo, vcc_lo, s0
	s_add_i32 vcc_lo, vcc_lo, 4
	s_lshl_b32 vcc_lo, vcc_lo, 7
	s_bfe_u32 m0, s3, 0x10008
	s_mul_i32 m0, m0, 0x12000
	s_add_i32 vcc_lo, vcc_lo, m0
	s_add_i32 vcc_lo, vcc_lo, 0x10010
	v_add_u32_e32 v184, vcc_lo, v168
	v_add_u32_e32 v185, vcc_lo, v169
	v_add_u32_e32 v186, vcc_lo, v170
	v_add_u32_e32 v187, vcc_lo, v171
	v_add_u32_e32 v188, vcc_lo, v172
	v_add_u32_e32 v189, vcc_lo, v173
	v_add_u32_e32 v190, vcc_lo, v174
	v_add_u32_e32 v191, vcc_lo, v175
	ds_read_b128 v[112:115], v146 offset:0
	ds_read_b128 v[116:119], v146 offset:4096
	ds_read_b128 v[120:123], v146 offset:8192
	ds_read_b128 v[124:127], v146 offset:12288
	ds_read_b128 v[128:131], v147 offset:0
	ds_read_b128 v[132:135], v147 offset:4096
	ds_read_b128 v[136:139], v147 offset:8192
	ds_read_b128 v[140:143], v147 offset:12288
	v_mov_b32_e32 v221, v220
	v_pk_add_f32 v[222:223], v[0:1], v[2:3]
	v_pk_add_f32 v[222:223], v[222:223], v[4:5]
	v_pk_add_f32 v[222:223], v[222:223], v[6:7]
	v_pk_add_f32 v[222:223], v[222:223], v[8:9]
	v_pk_add_f32 v[222:223], v[222:223], v[10:11]
	v_pk_add_f32 v[222:223], v[222:223], v[12:13]
	v_pk_add_f32 v[222:223], v[222:223], v[14:15]
	v_pk_add_f32 v[222:223], v[222:223], v[16:17]
	v_pk_add_f32 v[222:223], v[222:223], v[18:19]
	v_pk_add_f32 v[222:223], v[222:223], v[20:21]
	v_pk_add_f32 v[222:223], v[222:223], v[22:23]
	v_pk_add_f32 v[222:223], v[222:223], v[24:25]
	v_pk_add_f32 v[222:223], v[222:223], v[26:27]
	v_pk_add_f32 v[222:223], v[222:223], v[28:29]
	v_pk_add_f32 v[222:223], v[222:223], v[30:31]
	v_pk_mul_f32 v[32:33], v[32:33], v[220:221]
	v_pk_mul_f32 v[34:35], v[34:35], v[220:221]
	v_pk_mul_f32 v[36:37], v[36:37], v[220:221]
	v_pk_mul_f32 v[38:39], v[38:39], v[220:221]
	v_pk_mul_f32 v[40:41], v[40:41], v[220:221]
	v_pk_mul_f32 v[42:43], v[42:43], v[220:221]
	v_pk_mul_f32 v[44:45], v[44:45], v[220:221]
	v_pk_mul_f32 v[46:47], v[46:47], v[220:221]
	v_add_f32_e32 v203, v222, v223
	v_fma_f32 v201, v201, v220, v203
	v_cvt_pk_bf16_f32 v48, v0, v1
	v_cvt_pk_bf16_f32 v49, v2, v3
	v_cvt_pk_bf16_f32 v50, v4, v5
	v_cvt_pk_bf16_f32 v51, v6, v7
	v_cvt_pk_bf16_f32 v52, v8, v9
	v_cvt_pk_bf16_f32 v53, v10, v11
	v_cvt_pk_bf16_f32 v54, v12, v13
	v_cvt_pk_bf16_f32 v55, v14, v15
	v_cvt_pk_bf16_f32 v56, v16, v17
	v_cvt_pk_bf16_f32 v57, v18, v19
	v_cvt_pk_bf16_f32 v58, v20, v21
	v_cvt_pk_bf16_f32 v59, v22, v23
	v_cvt_pk_bf16_f32 v60, v24, v25
	v_cvt_pk_bf16_f32 v61, v26, v27
	v_cvt_pk_bf16_f32 v62, v28, v29
	v_cvt_pk_bf16_f32 v63, v30, v31
	s_waitcnt lgkmcnt(7)
	v_mfma_f32_16x16x32_bf16 v[32:35], v[112:115], v[48:51], v[32:35]
	ds_read_b128 v[112:115], v148 offset:0
	s_waitcnt lgkmcnt(7)
	v_mfma_f32_16x16x32_bf16 v[36:39], v[116:119], v[48:51], v[36:39]
	ds_read_b128 v[116:119], v148 offset:4096
	s_waitcnt lgkmcnt(7)
	v_mfma_f32_16x16x32_bf16 v[40:43], v[120:123], v[48:51], v[40:43]
	ds_read_b128 v[120:123], v148 offset:8192
	s_waitcnt lgkmcnt(7)
	v_mfma_f32_16x16x32_bf16 v[44:47], v[124:127], v[48:51], v[44:47]
	ds_read_b128 v[124:127], v148 offset:12288
	s_waitcnt lgkmcnt(7)
	v_mfma_f32_16x16x32_bf16 v[32:35], v[128:131], v[52:55], v[32:35]
	ds_read_b128 v[128:131], v149 offset:0
	s_waitcnt lgkmcnt(7)
	v_mfma_f32_16x16x32_bf16 v[36:39], v[132:135], v[52:55], v[36:39]
	ds_read_b128 v[132:135], v149 offset:4096
	s_waitcnt lgkmcnt(7)
	v_mfma_f32_16x16x32_bf16 v[40:43], v[136:139], v[52:55], v[40:43]
	ds_read_b128 v[136:139], v149 offset:8192
	s_waitcnt lgkmcnt(7)
	v_mfma_f32_16x16x32_bf16 v[44:47], v[140:143], v[52:55], v[44:47]
	ds_read_b128 v[140:143], v149 offset:12288
	s_waitcnt lgkmcnt(7)
	v_mfma_f32_16x16x32_bf16 v[32:35], v[112:115], v[56:59], v[32:35]
	s_waitcnt lgkmcnt(6)
	v_mfma_f32_16x16x32_bf16 v[36:39], v[116:119], v[56:59], v[36:39]
	s_waitcnt lgkmcnt(5)
	v_mfma_f32_16x16x32_bf16 v[40:43], v[120:123], v[56:59], v[40:43]
	s_waitcnt lgkmcnt(4)
	v_mfma_f32_16x16x32_bf16 v[44:47], v[124:127], v[56:59], v[44:47]
	s_waitcnt lgkmcnt(3)
	v_mfma_f32_16x16x32_bf16 v[32:35], v[128:131], v[60:63], v[32:35]
	s_waitcnt lgkmcnt(2)
	v_mfma_f32_16x16x32_bf16 v[36:39], v[132:135], v[60:63], v[36:39]
	s_waitcnt lgkmcnt(1)
	v_mfma_f32_16x16x32_bf16 v[40:43], v[136:139], v[60:63], v[40:43]
	s_waitcnt lgkmcnt(0)
	v_mfma_f32_16x16x32_bf16 v[44:47], v[140:143], v[60:63], v[44:47]
	s_waitcnt vmcnt(0)
	s_waitcnt lgkmcnt(0)
	s_barrier
; __device__ __forceinline__ void attn_phase(const Params& P, char* smem_raw) {
;     ...
;       __syncthreads();
;       f32x4 sacc[8];
; #pragma unroll
;       for (int t8 = 0; t8 < 8; ++t8) sacc[t8] = f32x4{0.f, 0.f, 0.f, 0.f};
; #pragma unroll
;       for (int s = 0; s < 2; ++s)
; #pragma unroll
;         for (int t8 = 0; t8 < 8; ++t8) {
;           const bf16x8 kf = *reinterpret_cast<const bf16x8*>(&sm_k[(t8 * 16 + (lane_c & 15)) * LDSS + s * 32 + (lane_c >> 4) * 8]);
;           sacc[t8] = __builtin_amdgcn_mfma_f32_16x16x32_bf16(qf[s], kf, sacc[t8], 0, 0, 0);
;         }
;       if (ck < 5) {
;         ATT_ISSUE(t, ck + 1)
;       } else if (t + VGRID < 8192) {
;         ATT_ISSUE(t + VGRID, 0)
;         ATT_QLOAD(t + VGRID)
;       }
;       if (ck < 4) {
;         const float* rb0 = sm_rpb + (rs + ck * 2 - r + 7) * 31;
; #pragma unroll
;         for (int t8 = 0; t8 < 8; ++t8)
; #pragma unroll
;           for (int reg = 0; reg < 4; ++reg)
;             sacc[t8][reg] += rb0[(t8 >> 2) * 31 + dco[reg][t8 & 3]];
;       }
; #pragma unroll
;       for (int reg = 0; reg < 4; ++reg) {
;         float mx = sacc[0][reg];
; #pragma unroll
;         for (int t8 = 1; t8 < 8; ++t8) mx = fmaxf(mx, sacc[t8][reg]);
;         mx = row16_max(mx);
	s_add_u32 s100, s12, 0x800
	s_addc_u32 s101, s13, 0
	s_add_u32 s0, s14, 0x0
	s_addc_u32 s1, s15, 0
	s_add_u32 m0, s18, 0x0
	s_nop 0
	v_mad_u64_u32 v[230:231], vcc, v154, 1, s[100:101]
	global_load_lds_dwordx4 v[230:231], off
	s_add_u32 m0, s18, 0x4000
	s_nop 0
	v_mad_u64_u32 v[232:233], vcc, v158, 1, s[0:1]
	global_load_lds_dwordx4 v[232:233], off
	s_add_u32 m0, s18, 0x400
	s_nop 0
	v_mad_u64_u32 v[230:231], vcc, v155, 1, s[100:101]
	global_load_lds_dwordx4 v[230:231], off
	s_add_u32 m0, s18, 0x4400
	s_nop 0
	v_mad_u64_u32 v[232:233], vcc, v159, 1, s[0:1]
	global_load_lds_dwordx4 v[232:233], off
	s_add_u32 m0, s18, 0x800
	s_nop 0
	v_mad_u64_u32 v[230:231], vcc, v156, 1, s[100:101]
	global_load_lds_dwordx4 v[230:231], off
	s_add_u32 m0, s18, 0x4800
	s_nop 0
	v_mad_u64_u32 v[232:233], vcc, v160, 1, s[0:1]
	global_load_lds_dwordx4 v[232:233], off
	s_add_u32 m0, s18, 0xc00
	s_nop 0
	v_mad_u64_u32 v[230:231], vcc, v157, 1, s[100:101]
	global_load_lds_dwordx4 v[230:231], off
	s_add_u32 m0, s18, 0x4c00
	s_nop 0
	v_mad_u64_u32 v[232:233], vcc, v161, 1, s[0:1]
	global_load_lds_dwordx4 v[232:233], off
	ds_read_b128 v[112:115], v144 offset:32768
	ds_read_b128 v[116:119], v145 offset:32768
	ds_read_b128 v[120:123], v144 offset:33280
	ds_read_b128 v[124:127], v145 offset:33280
	ds_read_b128 v[128:131], v144 offset:36864
	ds_read_b128 v[132:135], v145 offset:36864
	ds_read_b128 v[136:139], v144 offset:37376
	ds_read_b128 v[140:143], v145 offset:37376
	s_waitcnt lgkmcnt(7)
	v_mfma_f32_16x16x32_bf16 v[0:3], v[112:115], v[64:67], 0
	ds_read_b128 v[112:115], v144 offset:40960
	s_waitcnt lgkmcnt(7)
	v_mfma_f32_16x16x32_bf16 v[0:3], v[116:119], v[68:71], v[0:3]
	ds_read_b128 v[116:119], v145 offset:40960
	s_waitcnt lgkmcnt(7)
	v_mfma_f32_16x16x32_bf16 v[4:7], v[120:123], v[64:67], 0
	ds_read_b128 v[120:123], v144 offset:41472
	s_waitcnt lgkmcnt(7)
	v_mfma_f32_16x16x32_bf16 v[4:7], v[124:127], v[68:71], v[4:7]
	ds_read_b128 v[124:127], v145 offset:41472
	s_waitcnt lgkmcnt(7)
	v_mfma_f32_16x16x32_bf16 v[8:11], v[128:131], v[64:67], 0
	ds_read_b128 v[128:131], v144 offset:45056
	s_waitcnt lgkmcnt(7)
	v_mfma_f32_16x16x32_bf16 v[8:11], v[132:135], v[68:71], v[8:11]
	ds_read_b128 v[132:135], v145 offset:45056
	s_waitcnt lgkmcnt(7)
	v_mfma_f32_16x16x32_bf16 v[12:15], v[136:139], v[64:67], 0
	ds_read_b128 v[136:139], v144 offset:45568
	s_waitcnt lgkmcnt(7)
	v_mfma_f32_16x16x32_bf16 v[12:15], v[140:143], v[68:71], v[12:15]
	ds_read_b128 v[140:143], v145 offset:45568
	s_waitcnt lgkmcnt(7)
	v_mfma_f32_16x16x32_bf16 v[16:19], v[112:115], v[64:67], 0
	s_waitcnt lgkmcnt(6)
	v_mfma_f32_16x16x32_bf16 v[16:19], v[116:119], v[68:71], v[16:19]
	s_waitcnt lgkmcnt(5)
	v_mfma_f32_16x16x32_bf16 v[20:23], v[120:123], v[64:67], 0
	s_waitcnt lgkmcnt(4)
	v_mfma_f32_16x16x32_bf16 v[20:23], v[124:127], v[68:71], v[20:23]
	s_waitcnt lgkmcnt(3)
	v_mfma_f32_16x16x32_bf16 v[24:27], v[128:131], v[64:67], 0
	s_waitcnt lgkmcnt(2)
	v_mfma_f32_16x16x32_bf16 v[24:27], v[132:135], v[68:71], v[24:27]
	s_waitcnt lgkmcnt(1)
	v_mfma_f32_16x16x32_bf16 v[28:31], v[136:139], v[64:67], 0
	s_waitcnt lgkmcnt(0)
	v_mfma_f32_16x16x32_bf16 v[28:31], v[140:143], v[68:71], v[28:31]
	s_nop 7
	v_max3_f32 v203, v0, v1, v2
	v_max3_f32 v203, v203, v3, v4
	v_max3_f32 v203, v203, v5, v6
	v_max3_f32 v203, v203, v7, v8
	v_max3_f32 v203, v203, v9, v10
	v_max3_f32 v203, v203, v11, v12
	v_max3_f32 v203, v203, v13, v14
	v_max3_f32 v203, v203, v15, v16
	v_max3_f32 v203, v203, v17, v18
	v_max3_f32 v203, v203, v19, v20
	v_max3_f32 v203, v203, v21, v22
	v_max3_f32 v203, v203, v23, v24
	v_max3_f32 v203, v203, v25, v26
	v_max3_f32 v203, v203, v27, v28
	v_max3_f32 v203, v203, v29, v30
	v_max_f32_e32 v203, v203, v31
	v_mov_b32_e32 v205, v203
	s_nop 1
	v_permlane16_swap_b32_e32 v203, v205
	v_max_f32_e32 v203, v203, v205
	v_mov_b32_e32 v205, v203
	s_nop 1
	v_permlane32_swap_b32_e32 v203, v205
	v_max_f32_e32 v203, v203, v205
	v_max_f32_e32 v218, v200, v203
	v_sub_f32_e32 v220, v200, v218
	v_mov_b32_e32 v219, v218
	v_exp_f32_e32 v220, v220
	v_mov_b32_e32 v200, v218
	v_pk_add_f32 v[0:1], v[0:1], v[218:219] neg_lo:[0,1] neg_hi:[0,1]
	v_pk_add_f32 v[2:3], v[2:3], v[218:219] neg_lo:[0,1] neg_hi:[0,1]
	v_pk_add_f32 v[4:5], v[4:5], v[218:219] neg_lo:[0,1] neg_hi:[0,1]
	v_pk_add_f32 v[6:7], v[6:7], v[218:219] neg_lo:[0,1] neg_hi:[0,1]
	v_pk_add_f32 v[8:9], v[8:9], v[218:219] neg_lo:[0,1] neg_hi:[0,1]
	v_pk_add_f32 v[10:11], v[10:11], v[218:219] neg_lo:[0,1] neg_hi:[0,1]
	v_pk_add_f32 v[12:13], v[12:13], v[218:219] neg_lo:[0,1] neg_hi:[0,1]
	v_pk_add_f32 v[14:15], v[14:15], v[218:219] neg_lo:[0,1] neg_hi:[0,1]
	v_pk_add_f32 v[16:17], v[16:17], v[218:219] neg_lo:[0,1] neg_hi:[0,1]
	v_pk_add_f32 v[18:19], v[18:19], v[218:219] neg_lo:[0,1] neg_hi:[0,1]
	v_pk_add_f32 v[20:21], v[20:21], v[218:219] neg_lo:[0,1] neg_hi:[0,1]
	v_pk_add_f32 v[22:23], v[22:23], v[218:219] neg_lo:[0,1] neg_hi:[0,1]
	v_pk_add_f32 v[24:25], v[24:25], v[218:219] neg_lo:[0,1] neg_hi:[0,1]
	v_pk_add_f32 v[26:27], v[26:27], v[218:219] neg_lo:[0,1] neg_hi:[0,1]
	v_pk_add_f32 v[28:29], v[28:29], v[218:219] neg_lo:[0,1] neg_hi:[0,1]
	v_pk_add_f32 v[30:31], v[30:31], v[218:219] neg_lo:[0,1] neg_hi:[0,1]
	v_exp_f32_e32 v0, v0
	v_exp_f32_e32 v1, v1
	v_exp_f32_e32 v2, v2
	v_exp_f32_e32 v3, v3
	v_exp_f32_e32 v4, v4
	v_exp_f32_e32 v5, v5
	v_exp_f32_e32 v6, v6
	v_exp_f32_e32 v7, v7
	v_exp_f32_e32 v8, v8
	v_exp_f32_e32 v9, v9
	v_exp_f32_e32 v10, v10
	v_exp_f32_e32 v11, v11
	v_exp_f32_e32 v12, v12
	v_exp_f32_e32 v13, v13
	v_exp_f32_e32 v14, v14
	v_exp_f32_e32 v15, v15
	v_exp_f32_e32 v16, v16
	v_exp_f32_e32 v17, v17
	v_exp_f32_e32 v18, v18
	v_exp_f32_e32 v19, v19
	v_exp_f32_e32 v20, v20
; __device__ __forceinline__ void attn_phase(const Params& P, char* smem_raw) {
;     ...
;         float rsum = 0.f;
; #pragma unroll
;         for (int t8 = 0; t8 < 8; ++t8) {
;           const float p = __builtin_amdgcn_exp2f(sacc[t8][reg] - mnew);
;           rsum += p;
;           sm_p[(wid * 16 + (lane_c >> 4) * 4 + reg) * 136 + t8 * 16 + (lane_c & 15)] = f2bf(p);
;         }
;         rsum = row16_sum(rsum);
;         lrow[reg] = lrow[reg] * alpha + rsum;
; #pragma unroll
;         for (int td = 0; td < 4; ++td) o[td][reg] *= alpha;
;       }
;       asm volatile("s_waitcnt lgkmcnt(0)" ::: "memory");
; #pragma unroll
;       for (int s4 = 0; s4 < 4; ++s4) {
;         const bf16x8 pf = *reinterpret_cast<const bf16x8*>(&sm_p[(wid * 16 + (lane_c & 15)) * 136 + s4 * 32 + (lane_c >> 4) * 8]);
; #pragma unroll
;         for (int td = 0; td < 4; ++td) {
;           const bf16x8 vf = *reinterpret_cast<const bf16x8*>(&sm_vt[(td * 16 + (lane_c & 15)) * 136 + s4 * 32 + (lane_c >> 4) * 8]);
;           o[td] = __builtin_amdgcn_mfma_f32_16x16x32_bf16(pf, vf, o[td], 0, 0, 0);
;         }
;       }
;     }
;     u16* Ob = P.cat + ((long)b * 8192 + r * 64) * 1024 + h * 64;
; #pragma unroll
;     for (int td = 0; td < 4; ++td)
; #pragma unroll
;       for (int reg = 0; reg < 4; ++reg) {
;         const int rowl = wid * 16 + (lane >> 4) * 4 + reg;
;         Ob[(unsigned)(rowl * 1024 + td * 16 + (lane & 15))] = f2bf(o[td][reg] * __builtin_amdgcn_rcpf(lrow[reg]));
;       }
	v_exp_f32_e32 v21, v21
	v_exp_f32_e32 v22, v22
	v_exp_f32_e32 v23, v23
	v_exp_f32_e32 v24, v24
	v_exp_f32_e32 v25, v25
	v_exp_f32_e32 v26, v26
	v_exp_f32_e32 v27, v27
	v_exp_f32_e32 v28, v28
	v_exp_f32_e32 v29, v29
	v_exp_f32_e32 v30, v30
	v_exp_f32_e32 v31, v31
	ds_read_b128 v[112:115], v146 offset:32768
	ds_read_b128 v[116:119], v146 offset:36864
	ds_read_b128 v[120:123], v146 offset:40960
	ds_read_b128 v[124:127], v146 offset:45056
	ds_read_b128 v[128:131], v147 offset:32768
	ds_read_b128 v[132:135], v147 offset:36864
	ds_read_b128 v[136:139], v147 offset:40960
	ds_read_b128 v[140:143], v147 offset:45056
	v_mov_b32_e32 v221, v220
	v_pk_add_f32 v[222:223], v[0:1], v[2:3]
	v_pk_add_f32 v[222:223], v[222:223], v[4:5]
	v_pk_add_f32 v[222:223], v[222:223], v[6:7]
	v_pk_add_f32 v[222:223], v[222:223], v[8:9]
	v_pk_add_f32 v[222:223], v[222:223], v[10:11]
	v_pk_add_f32 v[222:223], v[222:223], v[12:13]
	v_pk_add_f32 v[222:223], v[222:223], v[14:15]
	v_pk_add_f32 v[222:223], v[222:223], v[16:17]
	v_pk_add_f32 v[222:223], v[222:223], v[18:19]
	v_pk_add_f32 v[222:223], v[222:223], v[20:21]
	v_pk_add_f32 v[222:223], v[222:223], v[22:23]
	v_pk_add_f32 v[222:223], v[222:223], v[24:25]
	v_pk_add_f32 v[222:223], v[222:223], v[26:27]
	v_pk_add_f32 v[222:223], v[222:223], v[28:29]
	v_pk_add_f32 v[222:223], v[222:223], v[30:31]
	v_pk_mul_f32 v[32:33], v[32:33], v[220:221]
	v_pk_mul_f32 v[34:35], v[34:35], v[220:221]
	v_pk_mul_f32 v[36:37], v[36:37], v[220:221]
	v_pk_mul_f32 v[38:39], v[38:39], v[220:221]
	v_pk_mul_f32 v[40:41], v[40:41], v[220:221]
	v_pk_mul_f32 v[42:43], v[42:43], v[220:221]
	v_pk_mul_f32 v[44:45], v[44:45], v[220:221]
	v_pk_mul_f32 v[46:47], v[46:47], v[220:221]
	v_add_f32_e32 v203, v222, v223
	v_fma_f32 v201, v201, v220, v203
	v_cvt_pk_bf16_f32 v48, v0, v1
	v_cvt_pk_bf16_f32 v49, v2, v3
	v_cvt_pk_bf16_f32 v50, v4, v5
	v_cvt_pk_bf16_f32 v51, v6, v7
	v_cvt_pk_bf16_f32 v52, v8, v9
	v_cvt_pk_bf16_f32 v53, v10, v11
	v_cvt_pk_bf16_f32 v54, v12, v13
	v_cvt_pk_bf16_f32 v55, v14, v15
	v_cvt_pk_bf16_f32 v56, v16, v17
	v_cvt_pk_bf16_f32 v57, v18, v19
	v_cvt_pk_bf16_f32 v58, v20, v21
	v_cvt_pk_bf16_f32 v59, v22, v23
	v_cvt_pk_bf16_f32 v60, v24, v25
	v_cvt_pk_bf16_f32 v61, v26, v27
	v_cvt_pk_bf16_f32 v62, v28, v29
	v_cvt_pk_bf16_f32 v63, v30, v31
	s_waitcnt lgkmcnt(7)
	v_mfma_f32_16x16x32_bf16 v[32:35], v[112:115], v[48:51], v[32:35]
	ds_read_b128 v[112:115], v148 offset:32768
	s_waitcnt lgkmcnt(7)
	v_mfma_f32_16x16x32_bf16 v[36:39], v[116:119], v[48:51], v[36:39]
	ds_read_b128 v[116:119], v148 offset:36864
	s_waitcnt lgkmcnt(7)
	v_mfma_f32_16x16x32_bf16 v[40:43], v[120:123], v[48:51], v[40:43]
	ds_read_b128 v[120:123], v148 offset:40960
	s_waitcnt lgkmcnt(7)
	v_mfma_f32_16x16x32_bf16 v[44:47], v[124:127], v[48:51], v[44:47]
	ds_read_b128 v[124:127], v148 offset:45056
	s_waitcnt lgkmcnt(7)
	v_mfma_f32_16x16x32_bf16 v[32:35], v[128:131], v[52:55], v[32:35]
	ds_read_b128 v[128:131], v149 offset:32768
	s_waitcnt lgkmcnt(7)
	v_mfma_f32_16x16x32_bf16 v[36:39], v[132:135], v[52:55], v[36:39]
	ds_read_b128 v[132:135], v149 offset:36864
	s_waitcnt lgkmcnt(7)
	v_mfma_f32_16x16x32_bf16 v[40:43], v[136:139], v[52:55], v[40:43]
	ds_read_b128 v[136:139], v149 offset:40960
	s_waitcnt lgkmcnt(7)
	v_mfma_f32_16x16x32_bf16 v[44:47], v[140:143], v[52:55], v[44:47]
	ds_read_b128 v[140:143], v149 offset:45056
	s_waitcnt lgkmcnt(7)
	v_mfma_f32_16x16x32_bf16 v[32:35], v[112:115], v[56:59], v[32:35]
	s_waitcnt lgkmcnt(6)
	v_mfma_f32_16x16x32_bf16 v[36:39], v[116:119], v[56:59], v[36:39]
	s_waitcnt lgkmcnt(5)
	v_mfma_f32_16x16x32_bf16 v[40:43], v[120:123], v[56:59], v[40:43]
	s_waitcnt lgkmcnt(4)
	v_mfma_f32_16x16x32_bf16 v[44:47], v[124:127], v[56:59], v[44:47]
	s_waitcnt lgkmcnt(3)
	v_mfma_f32_16x16x32_bf16 v[32:35], v[128:131], v[60:63], v[32:35]
	s_waitcnt lgkmcnt(2)
	v_mfma_f32_16x16x32_bf16 v[36:39], v[132:135], v[60:63], v[36:39]
	s_waitcnt lgkmcnt(1)
	v_mfma_f32_16x16x32_bf16 v[40:43], v[136:139], v[60:63], v[40:43]
	s_waitcnt lgkmcnt(0)
	v_mfma_f32_16x16x32_bf16 v[44:47], v[140:143], v[60:63], v[44:47]
	ds_read_b32 v0, v184 offset:384
	ds_read_b32 v1, v185 offset:384
	ds_read_b32 v2, v186 offset:384
	ds_read_b32 v3, v187 offset:384
	ds_read_b32 v4, v188 offset:384
	ds_read_b32 v5, v189 offset:384
	ds_read_b32 v6, v190 offset:384
	ds_read_b32 v7, v191 offset:384
	ds_read_b32 v8, v184 offset:512
	ds_read_b32 v9, v185 offset:512
	ds_read_b32 v10, v186 offset:512
	ds_read_b32 v11, v187 offset:512
	ds_read_b32 v12, v188 offset:512
	ds_read_b32 v13, v189 offset:512
	ds_read_b32 v14, v190 offset:512
	ds_read_b32 v15, v191 offset:512
	s_waitcnt vmcnt(0)
	s_waitcnt lgkmcnt(0)
	v_mov_b32_e32 v205, v201
	s_nop 1
	v_permlane16_swap_b32_e32 v201, v205
	v_add_f32_e32 v201, v201, v205
	v_mov_b32_e32 v205, v201
	s_nop 1
	v_permlane32_swap_b32_e32 v201, v205
	v_add_f32_e32 v201, v201, v205
	v_rcp_f32_e32 v203, v201
	s_nop 7
	v_mul_f32_e32 v32, v32, v203
	v_mul_f32_e32 v33, v33, v203
	v_mul_f32_e32 v34, v34, v203
	v_mul_f32_e32 v35, v35, v203
	v_mul_f32_e32 v36, v36, v203
	v_mul_f32_e32 v37, v37, v203
	v_mul_f32_e32 v38, v38, v203
	v_mul_f32_e32 v39, v39, v203
	v_mul_f32_e32 v40, v40, v203
	v_mul_f32_e32 v41, v41, v203
	v_mul_f32_e32 v42, v42, v203
	v_mul_f32_e32 v43, v43, v203
	v_mul_f32_e32 v44, v44, v203
	v_mul_f32_e32 v45, v45, v203
	v_mul_f32_e32 v46, v46, v203
	v_mul_f32_e32 v47, v47, v203
	v_cvt_pk_bf16_f32 v210, v32, v33
	v_cvt_pk_bf16_f32 v211, v34, v35
	v_cvt_pk_bf16_f32 v212, v36, v37
	v_cvt_pk_bf16_f32 v213, v38, v39
	v_cvt_pk_bf16_f32 v214, v40, v41
	v_cvt_pk_bf16_f32 v215, v42, v43
	v_cvt_pk_bf16_f32 v216, v44, v45
	v_cvt_pk_bf16_f32 v217, v46, v47
	global_store_dwordx2 v167, v[210:211], s[98:99] offset:0
	global_store_dwordx2 v167, v[212:213], s[98:99] offset:32
	global_store_dwordx2 v167, v[214:215], s[98:99] offset:64
	global_store_dwordx2 v167, v[216:217], s[98:99] offset:96
	v_mov_b32_e32 v200, 0xf149f2ca
	v_mov_b32_e32 v201, 0
	v_mov_b32_e32 v32, 0
	v_mov_b32_e32 v33, 0
	v_mov_b32_e32 v34, 0
	v_mov_b32_e32 v35, 0
	v_mov_b32_e32 v36, 0
	v_mov_b32_e32 v37, 0
	v_mov_b32_e32 v38, 0
	v_mov_b32_e32 v39, 0
	v_mov_b32_e32 v40, 0
	v_mov_b32_e32 v41, 0
	v_mov_b32_e32 v42, 0
	v_mov_b32_e32 v43, 0
	v_mov_b32_e32 v44, 0
	v_mov_b32_e32 v45, 0
	v_mov_b32_e32 v46, 0
	v_mov_b32_e32 v47, 0
	v_mov_b32_e32 v64, v72
	v_mov_b32_e32 v65, v73
	v_mov_b32_e32 v66, v74
	v_mov_b32_e32 v67, v75
	v_mov_b32_e32 v68, v76
	v_mov_b32_e32 v69, v77
	v_mov_b32_e32 v70, v78
	v_mov_b32_e32 v71, v79
	s_add_u32 s3, s3, 1
	s_and_b32 s0, s3, 0xff
	s_cmp_lt_u32 s0, 16
	s_cbranch_scc1 .Lmy_att_tile
	s_waitcnt vmcnt(0)
	s_branch .LBB0_1501
